# static s_setprio 1 for waves 4-7 also in the mLSTM units and in cross-attention (reset at phase exits)
# baseline (speedup 1.0000x reference)
; #define LAS __attribute__((address_space(3)))
; __device__ __forceinline__ void mlstm_unit(const Args& a, LAS unsigned char* lds, int b, int h, int tid_in, int wave, int lane_in) {
;     int tid = tid_in; asm volatile("" : "+v"(tid)); const int lane0 = tid & 63;
; __global__ void __launch_bounds__(512, 2) mk_fwd(Args a) {
;     ...
;         const int nml = (G > 64) ? 64 : (G > 1 ? G / 2 : 0);
;         if (vb < nml) { for (int u = vb; u < 64 * DUP_ML; u += nml) mlstm_unit(a5, lds, (u >> 2) & 15, u & 3, tid, wave, lane); }
.LBB0_980:
	v_readfirstlane_b32 s98, v252
	s_cmp_ge_u32 s98, 0x100
	s_cbranch_scc0 .Lprio2_ml
	s_setprio 1

; #define LAS __attribute__((address_space(3)))
; __global__ void __launch_bounds__(512, 2) mk_fwd(Args a) {
;     ...
;         if (vb < nml) { for (int u = vb; u < 64 * DUP_ML; u += nml) mlstm_unit(a5, lds, (u >> 2) & 15, u & 3, tid, wave, lane); }
;         {
;             LAS unsigned long long* maskl = (LAS unsigned long long*)(lds + 135168);
.LBB0_1071:
	s_setprio 0
	v_readlane_b32 s80, v254, 13
	v_readlane_b32 s81, v254, 14
	v_readlane_b32 s89, v254, 15
	v_readlane_b32 s85, v254, 16
	s_mov_b32 s86, s33

; __device__ __forceinline__ void xattn_unit(const Args& a, LAS unsigned char* lds, int b, int h, int qb, int tid, int wave, int lane) {
;     ...
;     const int fr = lane & 15, fq = lane >> 4; const size_t qrow = (size_t)b * SEQ + qb * 128 + 16 * wave + fr;
;     bf16x8 qf[8];
; #pragma unroll
;     for (int kk = 0; kk < 8; ++kk) qf[kk] = *(const GAS bf16x8*)(QX + qrow * DM + h * 256 + 32 * kk + 8 * fq);
;     u32x4 rr[2][4];
;     const unsigned vok = (unsigned)((tid >> 5) * DM + 8 * (tid & 31)) * 2u, vov = (unsigned)((tid >> 3) * MEMR + 8 * (tid & 7)) * 2u;
;     const GAS char* kxb = (const GAS char*)KX + ((size_t)b * 256 * DM + h * 256) * 2; const GAS char* vxb = (const GAS char*)VTX + ((size_t)h * 256 * MEMR + b * 256) * 2;
;     auto gload = [&](int j) {
;         if (j < 4) { const GAS char* p_ = kxb + (size_t)j * (64 * DM * 2);
; #pragma unroll
;             for (int i = 0; i < 4; ++i) rr[j & 1][i] = *(const GAS u32x4*)(p_ + (size_t)(vok + (unsigned)(i * 16 * DM * 2)));
;         } else { const GAS char* p_ = vxb + (size_t)(j - 4) * 128;
; #pragma unroll
;             for (int i = 0; i < 4; ++i) rr[j & 1][i] = *(const GAS u32x4*)(p_ + (size_t)(vov + (unsigned)(i * 64 * MEMR * 2)));
;         }
;     };
;     auto lstore = [&](int j) {
;         LAS bf16* base = (LAS bf16*)(lds + (j & 1) * STG);
;         if (j < 4) {
; #pragma unroll
;             for (int i = 0; i < 4; ++i) { const int id = tid + 512 * i; *(LAS u32x4*)(base + (id >> 5) * KS + 8 * (id & 31)) = rr[j & 1][i]; }
;         } else {
; #pragma unroll
;             for (int i = 0; i < 4; ++i) { const int id = tid + 512 * i; *(LAS u32x4*)(base + (id >> 3) * VS + 8 * (id & 7)) = rr[j & 1][i]; }
;         }
;     };
;     f32x4 S[16]; bf16x8 pf[8]; f32x4 O[16]; float l = 0.f;
; #pragma unroll
;     for (int i = 0; i < 16; ++i) { S[i] = (f32x4){0.f, 0.f, 0.f, 0.f}; O[i] = (f32x4){0.f, 0.f, 0.f, 0.f}; }
;     gload(0); gload(1); lstore(0); __syncthreads();
; #pragma unroll
; __global__ void __launch_bounds__(512, 2) mk_fwd(Args a) {
;     ...
;     if ((G & 7) == 0) { const int x = vb & 7, r = vb >> 3, nr = G >> 3;
;         const int per = (128 + nr - 1) / nr;
;         for (int w = r * per; w < 128 && w < (r + 1) * per; ++w) { int tu = threadIdx.x; asm volatile("" : "+v"(tu)); const int pr = x * 8 + (w >> 4); xattn_unit(a6, lds, pr >> 2, pr & 3, w & 15, tu, wave, tu & 63); } }
.LBB0_1515:
.LBB0_1516:
	s_ashr_i32 s0, s76, 3
	s_abs_i32 s1, s0
	v_cvt_f32_u32_e32 v0, s1
	s_sub_i32 s4, 0, s1
	s_add_i32 s3, s0, 0x7f
	s_xor_b32 s0, s3, s0
	v_rcp_iflag_f32_e32 v0, v0
	s_abs_i32 s3, s3
	s_ashr_i32 s2, s77, 3
	s_ashr_i32 s0, s0, 31
	v_mul_f32_e32 v0, 0x4f7ffffe, v0
	v_cvt_u32_f32_e32 v0, v0
	s_nop 0
	v_readfirstlane_b32 s5, v0
	s_mul_i32 s4, s4, s5
	s_mul_hi_u32 s4, s5, s4
	s_add_i32 s5, s5, s4
	s_mul_hi_u32 s4, s3, s5
	s_mul_i32 s5, s4, s1
	s_sub_i32 s3, s3, s5
	s_add_i32 s6, s4, 1
	s_sub_i32 s5, s3, s1
	s_cmp_ge_u32 s3, s1
	s_cselect_b32 s4, s6, s4
	s_cselect_b32 s3, s5, s3
	s_add_i32 s5, s4, 1
	s_cmp_ge_u32 s3, s1
	s_cselect_b32 s1, s5, s4
	s_xor_b32 s1, s1, s0
	s_sub_i32 s0, s1, s0
	s_mul_i32 s10, s0, s2
	s_add_i32 s0, s10, s0
	s_min_i32 s11, s0, 0x80
	s_cmp_ge_i32 s10, s11
	s_mov_b32 s1, 0
	s_cbranch_scc1 .LBB0_1519
	v_readlane_b32 s0, v254, 22
	s_lshl_b32 s12, s0, 3
	s_add_u32 s2, s72, 0x8400000
	s_addc_u32 s3, s73, 0
	s_add_u32 s13, s72, 0x1d000000
	s_addc_u32 s14, s73, 0
	s_add_u32 s15, s72, 0x1d800000
	s_addc_u32 s16, s73, 0
	s_add_u32 s4, s72, 0xc400000
	s_addc_u32 s5, s73, 0
	s_lshl_b32 s17, s10, 7
	v_mov_b32_e32 v201, 0
	s_movk_i32 s18, 0xf800
	s_movk_i32 s19, 0xe000
	s_movk_i32 s20, 0x210
	s_mov_b32 s21, 0xff61b1e6
	v_xor_b32_e32 v204, 32, v253
	s_movk_i32 s22, 0x90
	v_readfirstlane_b32 s98, v252
	s_cmp_ge_u32 s98, 0x100
	s_cbranch_scc0 .Lprio2_xa
	s_setprio 1
.Lprio2_xa:
.LBB0_1518:
	s_ashr_i32 s0, s10, 4
	s_and_b32 s6, s17, 0x780
	s_add_i32 s7, s0, s12
	v_mov_b32_e32 v200, v252
	s_and_b32 s23, s0, 3
	s_add_i32 s0, s6, s70
	s_ashr_i32 s6, s7, 2
	s_ashr_i32 s7, s6, 31
	v_lshlrev_b32_e32 v192, 4, v200
	v_add_u32_e32 v216, 0x200, v200
	v_lshlrev_b32_e32 v2, 6, v200
	v_and_b32_e32 v4, 0x1f0, v192
	v_ashrrev_i32_e32 v5, 5, v216
	s_lshl_b64 s[8:9], s[6:7], 11
	v_and_b32_e32 v213, 15, v200
	v_and_or_b32 v193, v2, s18, v4
	v_mul_lo_u32 v2, v5, s20
	s_add_u32 s0, s8, s0
	v_add3_u32 v212, 0, v2, v4
	s_addc_u32 s24, s9, 0
	v_or_b32_e32 v2, s0, v213
	s_lshl_b32 s0, s23, 9
	s_lshl_b64 s[8:9], s[6:7], 19
	v_ashrrev_i32_e32 v3, 5, v200
	v_add_u32_e32 v217, 0x400, v200
	s_add_u32 s8, s13, s8
	v_mul_lo_u32 v3, v3, s20
	v_ashrrev_i32_e32 v6, 5, v217
	s_addc_u32 s9, s14, s9
	s_lshl_b32 s6, s6, 8
	v_add3_u32 v211, 0, v3, v4
	v_mul_lo_u32 v3, v6, s20
	s_lshl_b32 s7, s23, 20
	s_ashr_i32 s23, s6, 31
	v_add3_u32 v224, 0, v3, v4
	v_mov_b32_e32 v3, s24
	s_add_u32 s6, s6, s7
	v_lshlrev_b64 v[202:203], 11, v[2:3]
	s_addc_u32 s7, s23, 0
	v_add_u32_e32 v218, 0x600, v200
	v_lshl_add_u64 v[2:3], s[2:3], 0, v[202:203]
	s_lshl_b64 s[6:7], s[6:7], 1
	v_mov_b32_e32 v1, v201
	v_and_b32_e32 v214, 63, v200
	v_and_b32_e32 v0, 48, v200
	v_ashrrev_i32_e32 v7, 5, v218
	v_lshl_add_u64 v[2:3], v[2:3], 0, s[0:1]
	s_add_u32 s8, s8, s0
	v_add_u32_e32 v8, 0, v0
	v_or_b32_e32 v215, 48, v214
	v_mul_lo_u32 v5, v7, s20
	v_lshl_add_u64 v[12:13], v[2:3], 0, v[0:1]
	s_addc_u32 s9, s9, 0
	v_mad_u32_u24 v210, v213, s20, v8
	v_mad_u32_u24 v209, v215, s20, v8
	v_add_u32_e32 v194, 0x8000, v193
	v_add_u32_e32 v195, 0x10000, v193
	v_add_u32_e32 v196, 0x18000, v193
	v_add3_u32 v225, 0, v5, v4
	global_load_dwordx4 v[156:159], v[12:13], off
	global_load_dwordx4 v[120:123], v[12:13], off offset:64
	global_load_dwordx4 v[112:115], v[12:13], off offset:128
	global_load_dwordx4 v[104:107], v[12:13], off offset:192
	global_load_dwordx4 v[28:31], v[12:13], off offset:256
	global_load_dwordx4 v[8:11], v[12:13], off offset:320
	global_load_dwordx4 v[4:7], v[12:13], off offset:384
	global_load_dwordx4 v[0:3], v[12:13], off offset:448
	s_nop 0
	global_load_dwordx4 v[12:15], v193, s[8:9]
	global_load_dwordx4 v[16:19], v194, s[8:9]
	global_load_dwordx4 v[20:23], v195, s[8:9]
	global_load_dwordx4 v[24:27], v196, s[8:9]
	s_add_u32 s6, s15, s6
	s_addc_u32 s7, s16, s7
	s_add_u32 s24, s8, 0x20000
	s_addc_u32 s25, s9, 0
	global_load_dwordx4 v[32:35], v193, s[24:25]
	global_load_dwordx4 v[36:39], v194, s[24:25]
	global_load_dwordx4 v[40:43], v195, s[24:25]
	global_load_dwordx4 v[44:47], v196, s[24:25]
	s_add_u32 s24, s8, 0x40000
	s_addc_u32 s25, s9, 0
	s_add_u32 s8, s8, 0x60000
	s_addc_u32 s9, s9, 0
	v_and_b32_e32 v219, 0x70, v192
	v_lshrrev_b32_e32 v216, 3, v216
	v_cmp_lt_i32_e32 vcc, v227, v226
	s_add_i32 s10, s10, 1
	s_addk_i32 s17, 0x80
	s_cmp_ge_i32 s10, s11
	s_waitcnt vmcnt(0)
	ds_write_b128 v211, v[12:15]
	ds_write_b128 v212, v[16:19]
	ds_write_b128 v224, v[20:23]
	ds_write_b128 v225, v[24:27]
	s_waitcnt lgkmcnt(0)
	s_barrier
	global_load_dwordx4 v[12:15], v193, s[24:25]
	global_load_dwordx4 v[16:19], v194, s[24:25]
	global_load_dwordx4 v[20:23], v195, s[24:25]
	global_load_dwordx4 v[24:27], v196, s[24:25]
	ds_read_b128 v[48:51], v210
	ds_read_b128 v[52:55], v210 offset:64
	ds_read_b128 v[56:59], v210 offset:128
	ds_read_b128 v[60:63], v210 offset:192
	ds_read_b128 v[64:67], v210 offset:256
	ds_read_b128 v[68:71], v210 offset:320
	ds_read_b128 v[72:75], v210 offset:384
	ds_read_b128 v[76:79], v210 offset:448
	ds_read_b128 v[80:83], v210 offset:8448
	ds_read_b128 v[84:87], v210 offset:8512
	ds_read_b128 v[88:91], v210 offset:8576
	ds_read_b128 v[92:95], v210 offset:8640
	ds_read_b128 v[96:99], v210 offset:8704
	ds_read_b128 v[100:103], v210 offset:8768
	ds_read_b128 v[108:111], v210 offset:8832
	ds_read_b128 v[116:119], v210 offset:8896
	ds_read_b128 v[124:127], v210 offset:16896
	ds_read_b128 v[128:131], v210 offset:16960
	s_waitcnt lgkmcnt(14)
	v_mfma_f32_16x16x32_bf16 v[48:51], v[48:51], v[156:159], 0
	ds_read_b128 v[132:135], v210 offset:17024
	ds_read_b128 v[136:139], v210 offset:17088
	ds_read_b128 v[140:143], v209
	ds_read_b128 v[144:147], v210 offset:17152
	ds_read_b128 v[148:151], v210 offset:17216
	ds_read_b128 v[152:155], v210 offset:17280
	ds_read_b128 v[160:163], v210 offset:17344
	ds_read_b128 v[164:167], v209 offset:64
	ds_read_b128 v[168:171], v209 offset:128
	s_waitcnt lgkmcnt(14)
	v_mfma_f32_16x16x32_bf16 v[80:83], v[80:83], v[156:159], 0
	ds_read_b128 v[172:175], v209 offset:192
	ds_read_b128 v[176:179], v209 offset:256
	ds_read_b128 v[180:183], v209 offset:320
	s_waitcnt lgkmcnt(13)
	v_mfma_f32_16x16x32_bf16 v[124:127], v[124:127], v[156:159], 0
	v_mfma_f32_16x16x32_bf16 v[48:51], v[52:55], v[120:123], v[48:51]
	ds_read_b128 v[52:55], v209 offset:384
	ds_read_b128 v[184:187], v209 offset:448
	ds_write_b128 v211, v[32:35] offset:36864
	ds_write_b128 v212, v[36:39] offset:36864
	ds_write_b128 v224, v[40:43] offset:36864
	ds_write_b128 v225, v[44:47] offset:36864
	v_mfma_f32_16x16x32_bf16 v[32:35], v[84:87], v[120:123], v[80:83]
	s_waitcnt lgkmcnt(0)
	s_barrier
; #define LAS __attribute__((address_space(3)))
; __device__ __forceinline__ f32x4 mfma16(bf16x8 a, bf16x8 b, f32x4 c) { return __builtin_amdgcn_mfma_f32_16x16x32_bf16(a, b, c, 0, 0, 0); }
; __device__ __forceinline__ bf16x8 pack8(f32x4 a, f32x4 b) { u32x4 w; w.x = pk2(a[0], a[1]); w.y = pk2(a[2], a[3]); w.z = pk2(b[0], b[1]); w.w = pk2(b[2], b[3]); return __builtin_bit_cast(bf16x8, w); }
; __device__ __forceinline__ void xattn_unit(const Args& a, LAS unsigned char* lds, int b, int h, int qb, int tid, int wave, int lane) {
;     ...
;     for (int j = 0; j < 8; ++j) {
;         if (j < 6) gload(j + 2);
;         const LAS bf16* base = (const LAS bf16*)(lds + (j & 1) * STG);
;         if (j < 4) {
; #pragma unroll
;             for (int rt = 0; rt < 4; ++rt)
; #pragma unroll
;                 for (int kk = 0; kk < 8; ++kk) S[4 * j + rt] = mfma16(*(const LAS bf16x8*)(base + (16 * rt + fr) * KS + 32 * kk + 8 * fq), qf[kk], S[4 * j + rt]);
;             if (j == 3) {
;                 float mx = -3.0e38f;
; #pragma unroll
;                 for (int i = 0; i < 16; ++i) mx = fmaxf(mx, fmaxf(fmaxf(S[i][0], S[i][1]), fmaxf(S[i][2], S[i][3])));
;                 mx = fmaxf(mx, __shfl_xor(mx, 16)); mx = fmaxf(mx, __shfl_xor(mx, 32));
; #pragma unroll
;                 for (int i = 0; i < 16; ++i)
; #pragma unroll
;                     for (int k = 0; k < 4; ++k) { S[i][k] = __builtin_amdgcn_exp2f(S[i][k] - mx); l += S[i][k]; }
;                 l += __shfl_xor(l, 16); l += __shfl_xor(l, 32);
; #pragma unroll
;                 for (int c2 = 0; c2 < 8; ++c2) pf[c2] = pack8(S[2 * c2], S[2 * c2 + 1]);
;             }
;         } else {
;             const int mt = j - 4;
; #pragma unroll
;             for (int dt = 0; dt < 16; ++dt) {
;                 const LAS bf16* vr = base + (16 * dt + fr) * VS + 4 * fq;
;                 O[dt] = mfma16(cat8(*(const LAS u32x2*)vr, *(const LAS u32x2*)(vr + 16)), pf[2 * mt], O[dt]);
;                 O[dt] = mfma16(cat8(*(const LAS u32x2*)(vr + 32), *(const LAS u32x2*)(vr + 48)), pf[2 * mt + 1], O[dt]);
;             }
;         }
;         if (j < 7) lstore(j + 1);
;         __syncthreads();
	ds_read_b128 v[44:47], v210 offset:36864
	ds_read_b128 v[80:83], v210 offset:36928
	v_mfma_f32_16x16x32_bf16 v[140:143], v[140:143], v[156:159], 0
	v_mfma_f32_16x16x32_bf16 v[36:39], v[128:131], v[120:123], v[124:127]
	ds_read_b128 v[84:87], v210 offset:45312
	s_nop 1
	ds_read_b128 v[124:127], v210 offset:45376
	s_waitcnt lgkmcnt(3)
	v_mfma_f32_16x16x32_bf16 v[44:47], v[44:47], v[156:159], 0
	v_mfma_f32_16x16x32_bf16 v[48:51], v[56:59], v[112:115], v[48:51]
	v_mfma_f32_16x16x32_bf16 v[40:43], v[164:167], v[120:123], v[140:143]
	ds_read_b128 v[128:131], v210 offset:53760
	s_nop 1
	ds_read_b128 v[140:143], v210 offset:53824
	ds_read_b128 v[164:167], v209 offset:36864
	ds_read_b128 v[188:191], v209 offset:36928
	s_waitcnt lgkmcnt(5)
	v_mfma_f32_16x16x32_bf16 v[84:87], v[84:87], v[156:159], 0
	v_mfma_f32_16x16x32_bf16 v[32:35], v[88:91], v[112:115], v[32:35]
	v_mfma_f32_16x16x32_bf16 v[44:47], v[80:83], v[120:123], v[44:47]
	v_mfma_f32_16x16x32_bf16 v[48:51], v[60:63], v[104:107], v[48:51]
	ds_read_b128 v[60:63], v210 offset:36992
	ds_read_b128 v[88:91], v210 offset:37056
	s_waitcnt lgkmcnt(5)
	v_mfma_f32_16x16x32_bf16 v[128:131], v[128:131], v[156:159], 0
	v_mfma_f32_16x16x32_bf16 v[56:59], v[124:127], v[120:123], v[84:87]
	v_mfma_f32_16x16x32_bf16 v[32:35], v[92:95], v[104:107], v[32:35]
	s_waitcnt lgkmcnt(1)
	v_mfma_f32_16x16x32_bf16 v[44:47], v[60:63], v[112:115], v[44:47]
	ds_read_b128 v[60:63], v210 offset:45440
	ds_read_b128 v[92:95], v210 offset:45504
	v_mfma_f32_16x16x32_bf16 v[164:167], v[164:167], v[156:159], 0
	v_mfma_f32_16x16x32_bf16 v[80:83], v[140:143], v[120:123], v[128:131]
	s_waitcnt lgkmcnt(1)
	v_mfma_f32_16x16x32_bf16 v[56:59], v[60:63], v[112:115], v[56:59]
	ds_read_b128 v[60:63], v210 offset:53888
	ds_read_b128 v[124:127], v210 offset:53952
	v_mfma_f32_16x16x32_bf16 v[84:87], v[188:191], v[120:123], v[164:167]
	s_waitcnt lgkmcnt(1)
	v_mfma_f32_16x16x32_bf16 v[60:63], v[60:63], v[112:115], v[80:83]
	s_nop 2
	ds_read_b128 v[80:83], v209 offset:36992
	ds_read_b128 v[128:131], v209 offset:37056
	v_mfma_f32_16x16x32_bf16 v[40:43], v[168:171], v[112:115], v[40:43]
	s_waitcnt lgkmcnt(1)
	v_mfma_f32_16x16x32_bf16 v[80:83], v[80:83], v[112:115], v[84:87]
	v_mfma_f32_16x16x32_bf16 v[48:51], v[64:67], v[28:31], v[48:51]
	v_mfma_f32_16x16x32_bf16 v[40:43], v[172:175], v[104:107], v[40:43]
	v_mfma_f32_16x16x32_bf16 v[44:47], v[88:91], v[104:107], v[44:47]
	s_waitcnt lgkmcnt(0)
	v_mfma_f32_16x16x32_bf16 v[64:67], v[128:131], v[104:107], v[80:83]
	v_mfma_f32_16x16x32_bf16 v[48:51], v[68:71], v[8:11], v[48:51]
	ds_read_b128 v[68:71], v210 offset:37120
	s_nop 0
	ds_read_b128 v[80:83], v210 offset:37184
	v_mfma_f32_16x16x32_bf16 v[32:35], v[96:99], v[28:31], v[32:35]
	v_mfma_f32_16x16x32_bf16 v[40:43], v[176:179], v[28:31], v[40:43]
	v_mfma_f32_16x16x32_bf16 v[56:59], v[92:95], v[104:107], v[56:59]
	s_waitcnt lgkmcnt(1)
	v_mfma_f32_16x16x32_bf16 v[44:47], v[68:71], v[28:31], v[44:47]
	ds_read_b128 v[68:71], v210 offset:45568
	ds_read_b128 v[84:87], v210 offset:45632
	v_mfma_f32_16x16x32_bf16 v[36:39], v[132:135], v[112:115], v[36:39]
	v_mfma_f32_16x16x32_bf16 v[60:63], v[124:127], v[104:107], v[60:63]
	v_mfma_f32_16x16x32_bf16 v[32:35], v[100:103], v[8:11], v[32:35]
	v_mfma_f32_16x16x32_bf16 v[40:43], v[180:183], v[8:11], v[40:43]
	s_waitcnt lgkmcnt(1)
	v_mfma_f32_16x16x32_bf16 v[56:59], v[68:71], v[28:31], v[56:59]
	ds_read_b128 v[68:71], v210 offset:54016
	ds_read_b128 v[88:91], v210 offset:54080
	v_mfma_f32_16x16x32_bf16 v[36:39], v[136:139], v[104:107], v[36:39]
	s_waitcnt lgkmcnt(1)
	v_mfma_f32_16x16x32_bf16 v[60:63], v[68:71], v[28:31], v[60:63]
	ds_read_b128 v[68:71], v209 offset:37120
	ds_read_b128 v[92:95], v209 offset:37184
	v_mfma_f32_16x16x32_bf16 v[48:51], v[72:75], v[4:7], v[48:51]
	v_mfma_f32_16x16x32_bf16 v[32:35], v[108:111], v[4:7], v[32:35]
	v_mfma_f32_16x16x32_bf16 v[52:55], v[52:55], v[4:7], v[40:43]
	v_mfma_f32_16x16x32_bf16 v[36:39], v[144:147], v[28:31], v[36:39]
	s_waitcnt lgkmcnt(1)
	v_mfma_f32_16x16x32_bf16 v[64:67], v[68:71], v[28:31], v[64:67]
	v_mfma_f32_16x16x32_bf16 v[68:71], v[80:83], v[8:11], v[44:47]
	v_mfma_f32_16x16x32_bf16 v[44:47], v[76:79], v[0:3], v[48:51]
	v_mfma_f32_16x16x32_bf16 v[40:43], v[116:119], v[0:3], v[32:35]
	v_mfma_f32_16x16x32_bf16 v[32:35], v[184:187], v[0:3], v[52:55]
	s_nop 0
	ds_read_b128 v[48:51], v210 offset:37248
	s_nop 0
	ds_read_b128 v[52:55], v210 offset:37312
	v_mfma_f32_16x16x32_bf16 v[36:39], v[148:151], v[8:11], v[36:39]
	v_mfma_f32_16x16x32_bf16 v[56:59], v[84:87], v[8:11], v[56:59]
	v_lshlrev_b32_e32 v84, 10, v200
	v_and_or_b32 v205, v84, s19, v219
	v_add_u32_e32 v206, 0x80000, v205
	s_waitcnt lgkmcnt(1)
	v_mfma_f32_16x16x32_bf16 v[48:51], v[48:51], v[4:7], v[68:71]
	s_nop 2
	ds_read_b128 v[68:71], v210 offset:45696
	ds_read_b128 v[72:75], v210 offset:45760
	v_add_u32_e32 v207, 0x100000, v205
	v_add_u32_e32 v208, 0x180000, v205
	v_mfma_f32_16x16x32_bf16 v[36:39], v[152:155], v[4:7], v[36:39]
	v_mfma_f32_16x16x32_bf16 v[60:63], v[88:91], v[8:11], v[60:63]
	s_waitcnt lgkmcnt(1)
	v_mfma_f32_16x16x32_bf16 v[56:59], v[68:71], v[4:7], v[56:59]
	ds_read_b128 v[68:71], v210 offset:54144
	ds_read_b128 v[76:79], v210 offset:54208
	v_mfma_f32_16x16x32_bf16 v[36:39], v[160:163], v[0:3], v[36:39]
	s_waitcnt lgkmcnt(1)
	v_mfma_f32_16x16x32_bf16 v[60:63], v[68:71], v[4:7], v[60:63]
	ds_read_b128 v[68:71], v209 offset:37248
	ds_read_b128 v[80:83], v209 offset:37312
	global_load_dwordx4 v[160:163], v193, s[8:9]
	global_load_dwordx4 v[164:167], v194, s[8:9]
	global_load_dwordx4 v[168:171], v195, s[8:9]
	global_load_dwordx4 v[172:175], v196, s[8:9]
	v_mfma_f32_16x16x32_bf16 v[64:67], v[92:95], v[8:11], v[64:67]
	s_waitcnt vmcnt(7)
	ds_write_b128 v211, v[12:15]
	s_waitcnt vmcnt(6)
	ds_write_b128 v212, v[16:19]
	s_waitcnt vmcnt(5)
	ds_write_b128 v224, v[20:23]
	s_waitcnt vmcnt(4)
	ds_write_b128 v225, v[24:27]
	s_waitcnt lgkmcnt(0)
	s_barrier
; #define LAS __attribute__((address_space(3)))
; __device__ __forceinline__ f32x4 mfma16(bf16x8 a, bf16x8 b, f32x4 c) { return __builtin_amdgcn_mfma_f32_16x16x32_bf16(a, b, c, 0, 0, 0); }
; __device__ __forceinline__ bf16x8 pack8(f32x4 a, f32x4 b) { u32x4 w; w.x = pk2(a[0], a[1]); w.y = pk2(a[2], a[3]); w.z = pk2(b[0], b[1]); w.w = pk2(b[2], b[3]); return __builtin_bit_cast(bf16x8, w); }
; __device__ __forceinline__ void xattn_unit(const Args& a, LAS unsigned char* lds, int b, int h, int qb, int tid, int wave, int lane) {
;     ...
;     for (int j = 0; j < 8; ++j) {
;         if (j < 6) gload(j + 2);
;         const LAS bf16* base = (const LAS bf16*)(lds + (j & 1) * STG);
;         if (j < 4) {
; #pragma unroll
;             for (int rt = 0; rt < 4; ++rt)
; #pragma unroll
;                 for (int kk = 0; kk < 8; ++kk) S[4 * j + rt] = mfma16(*(const LAS bf16x8*)(base + (16 * rt + fr) * KS + 32 * kk + 8 * fq), qf[kk], S[4 * j + rt]);
;             if (j == 3) {
;                 float mx = -3.0e38f;
; #pragma unroll
;                 for (int i = 0; i < 16; ++i) mx = fmaxf(mx, fmaxf(fmaxf(S[i][0], S[i][1]), fmaxf(S[i][2], S[i][3])));
;                 mx = fmaxf(mx, __shfl_xor(mx, 16)); mx = fmaxf(mx, __shfl_xor(mx, 32));
; #pragma unroll
;                 for (int i = 0; i < 16; ++i)
; #pragma unroll
;                     for (int k = 0; k < 4; ++k) { S[i][k] = __builtin_amdgcn_exp2f(S[i][k] - mx); l += S[i][k]; }
;                 l += __shfl_xor(l, 16); l += __shfl_xor(l, 32);
; #pragma unroll
;                 for (int c2 = 0; c2 < 8; ++c2) pf[c2] = pack8(S[2 * c2], S[2 * c2 + 1]);
;             }
;         } else {
;             const int mt = j - 4;
; #pragma unroll
;             for (int dt = 0; dt < 16; ++dt) {
;                 const LAS bf16* vr = base + (16 * dt + fr) * VS + 4 * fq;
;                 O[dt] = mfma16(cat8(*(const LAS u32x2*)vr, *(const LAS u32x2*)(vr + 16)), pf[2 * mt], O[dt]);
;                 O[dt] = mfma16(cat8(*(const LAS u32x2*)(vr + 32), *(const LAS u32x2*)(vr + 48)), pf[2 * mt + 1], O[dt]);
;             }
;         }
;         if (j < 7) lstore(j + 1);
;         __syncthreads();
	v_mfma_f32_16x16x32_bf16 v[64:67], v[68:71], v[4:7], v[64:67]
	global_load_dwordx4 v[12:15], v205, s[6:7]
	global_load_dwordx4 v[16:19], v206, s[6:7]
	global_load_dwordx4 v[20:23], v207, s[6:7]
	global_load_dwordx4 v[24:27], v208, s[6:7]
	v_mfma_f32_16x16x32_bf16 v[52:55], v[52:55], v[0:3], v[48:51]
	v_mfma_f32_16x16x32_bf16 v[56:59], v[72:75], v[0:3], v[56:59]
	v_mfma_f32_16x16x32_bf16 v[60:63], v[76:79], v[0:3], v[60:63]
	v_mfma_f32_16x16x32_bf16 v[48:51], v[80:83], v[0:3], v[64:67]
	ds_read_b128 v[76:79], v210
	ds_read_b128 v[84:87], v210 offset:64
	ds_read_b128 v[220:223], v210 offset:128
	ds_read_b128 v[132:135], v210 offset:192
	ds_read_b128 v[124:127], v210 offset:256
	ds_read_b128 v[116:119], v210 offset:320
	ds_read_b128 v[72:75], v210 offset:384
	ds_read_b128 v[64:67], v210 offset:448
	ds_read_b128 v[88:91], v210 offset:8448
	ds_read_b128 v[176:179], v210 offset:8512
	ds_read_b128 v[228:231], v210 offset:8576
	ds_read_b128 v[140:143], v210 offset:8640
	ds_read_b128 v[128:131], v210 offset:8704
	ds_read_b128 v[108:111], v210 offset:8768
	ds_read_b128 v[80:83], v210 offset:8832
	ds_read_b128 v[68:71], v210 offset:8896
	ds_read_b128 v[92:95], v210 offset:16896
	ds_read_b128 v[180:183], v210 offset:16960
	ds_read_b128 v[232:235], v210 offset:17024
	ds_read_b128 v[148:151], v210 offset:17088
	ds_read_b128 v[96:99], v209
	s_waitcnt lgkmcnt(14)
	v_mfma_f32_16x16x32_bf16 v[184:187], v[76:79], v[156:159], 0
	s_waitcnt lgkmcnt(12)
	v_mfma_f32_16x16x32_bf16 v[188:191], v[88:91], v[156:159], 0
	ds_read_b128 v[136:139], v210 offset:17152
	ds_read_b128 v[100:103], v210 offset:17216
	ds_read_b128 v[88:91], v210 offset:17280
	ds_read_b128 v[76:79], v210 offset:17344
	ds_read_b128 v[196:199], v209 offset:64
	ds_read_b128 v[236:239], v209 offset:128
	s_waitcnt lgkmcnt(6)
	v_mfma_f32_16x16x32_bf16 v[240:243], v[96:99], v[156:159], 0
	ds_read_b128 v[152:155], v209 offset:192
	ds_read_b128 v[144:147], v209 offset:256
	ds_read_b128 v[96:99], v209 offset:320
	v_mfma_f32_16x16x32_bf16 v[192:195], v[92:95], v[156:159], 0
	v_mfma_f32_16x16x32_bf16 v[244:247], v[84:87], v[120:123], v[184:187]
	ds_read_b128 v[92:95], v209 offset:384
	ds_read_b128 v[84:87], v209 offset:448
	s_waitcnt vmcnt(7)
	ds_write_b128 v211, v[160:163] offset:36864
	s_waitcnt vmcnt(6)
	ds_write_b128 v212, v[164:167] offset:36864
	s_waitcnt vmcnt(5)
	ds_write_b128 v224, v[168:171] offset:36864
	s_waitcnt vmcnt(4)
	ds_write_b128 v225, v[172:175] offset:36864
	s_waitcnt lgkmcnt(0)
	s_barrier
	v_mfma_f32_16x16x32_bf16 v[172:175], v[196:199], v[120:123], v[240:243]
	ds_read_b128 v[164:167], v210 offset:36864
	s_nop 1
	ds_read_b128 v[240:243], v210 offset:36928
	v_cndmask_b32_e32 v211, v253, v227, vcc
	v_lshlrev_b32_e32 v211, 2, v211
	s_waitcnt lgkmcnt(1)
	v_mfma_f32_16x16x32_bf16 v[248:251], v[164:167], v[156:159], 0
	ds_read_b128 v[164:167], v210 offset:45312
	ds_read_b128 v[184:187], v210 offset:45376
	v_cmp_lt_i32_e32 vcc, v204, v226
	v_mfma_f32_16x16x32_bf16 v[160:163], v[176:179], v[120:123], v[188:191]
	s_nop 0
	v_cndmask_b32_e32 v212, v253, v204, vcc
	v_lshlrev_b32_e32 v212, 2, v212
	v_mfma_f32_16x16x32_bf16 v[168:171], v[180:183], v[120:123], v[192:195]
	s_waitcnt lgkmcnt(1)
	v_mfma_f32_16x16x32_bf16 v[188:191], v[164:167], v[156:159], 0
	ds_read_b128 v[164:167], v210 offset:53760
	ds_read_b128 v[192:195], v210 offset:53824
	s_waitcnt lgkmcnt(1)
	v_mfma_f32_16x16x32_bf16 v[196:199], v[164:167], v[156:159], 0
	ds_read_b128 v[164:167], v209 offset:36864
	ds_read_b128 v[176:179], v209 offset:36928
	s_waitcnt lgkmcnt(1)
	v_mfma_f32_16x16x32_bf16 v[180:183], v[164:167], v[156:159], 0
	v_mfma_f32_16x16x32_bf16 v[164:167], v[220:223], v[112:115], v[244:247]
	v_lshrrev_b32_e32 v220, 1, v200
	v_lshrrev_b32_e32 v221, 3, v200
	v_and_b32_e32 v200, 24, v220
	v_mfma_f32_16x16x32_bf16 v[160:163], v[228:231], v[112:115], v[160:163]
	v_or_b32_e32 v222, 0x70, v214
	v_or_b32_e32 v223, 0xf0, v214
	v_mul_lo_u32 v220, v221, s22
	v_mfma_f32_16x16x32_bf16 v[156:159], v[232:235], v[112:115], v[168:171]
	v_mfma_f32_16x16x32_bf16 v[168:171], v[236:239], v[112:115], v[172:175]
	v_mfma_f32_16x16x32_bf16 v[184:187], v[184:187], v[120:123], v[188:191]
	v_mfma_f32_16x16x32_bf16 v[188:191], v[192:195], v[120:123], v[196:199]
	v_lshrrev_b32_e32 v192, 3, v217
	v_lshrrev_b32_e32 v193, 3, v218
	v_mfma_f32_16x16x32_bf16 v[172:175], v[240:243], v[120:123], v[248:251]
	s_waitcnt lgkmcnt(0)
	v_mfma_f32_16x16x32_bf16 v[120:123], v[176:179], v[120:123], v[180:183]
	v_mul_lo_u32 v178, v193, s22
	v_or_b32_e32 v177, 0xb0, v214
	v_add3_u32 v176, 0, v220, v219
	v_mfma_f32_16x16x32_bf16 v[132:135], v[132:135], v[104:107], v[164:167]
	s_nop 2
	v_mul_lo_u32 v164, v216, s22
	v_mul_lo_u32 v165, v192, s22
	v_mfma_f32_16x16x32_bf16 v[140:143], v[140:143], v[104:107], v[160:163]
	s_nop 2
	v_add3_u32 v160, 0, v164, v219
	v_add3_u32 v161, 0, v165, v219
	v_mfma_f32_16x16x32_bf16 v[164:167], v[148:151], v[104:107], v[156:159]
	v_add3_u32 v148, 0, v178, v219
	v_add_u32_e32 v162, 0, v200
	v_mad_u32_u24 v151, v215, s22, v162
	v_mfma_f32_16x16x32_bf16 v[168:171], v[152:155], v[104:107], v[168:171]
	ds_read_b128 v[152:155], v210 offset:36992
	ds_read_b128 v[178:181], v210 offset:37056
	v_mad_u32_u24 v156, v213, s22, v162
	v_mad_u32_u24 v150, v177, s22, v162
	s_waitcnt lgkmcnt(1)
	v_mfma_f32_16x16x32_bf16 v[172:175], v[152:155], v[112:115], v[172:175]
	ds_read_b128 v[152:155], v210 offset:45440
	ds_read_b128 v[192:195], v210 offset:45504
	v_mad_u32_u24 v149, v223, s22, v162
	v_add_u32_e32 v158, 0x2000, v156
	s_waitcnt lgkmcnt(1)
; #define LAS __attribute__((address_space(3)))
; __device__ __forceinline__ f32x4 mfma16(bf16x8 a, bf16x8 b, f32x4 c) { return __builtin_amdgcn_mfma_f32_16x16x32_bf16(a, b, c, 0, 0, 0); }
; __device__ __forceinline__ bf16x8 pack8(f32x4 a, f32x4 b) { u32x4 w; w.x = pk2(a[0], a[1]); w.y = pk2(a[2], a[3]); w.z = pk2(b[0], b[1]); w.w = pk2(b[2], b[3]); return __builtin_bit_cast(bf16x8, w); }
; __device__ __forceinline__ void xattn_unit(const Args& a, LAS unsigned char* lds, int b, int h, int qb, int tid, int wave, int lane) {
;     ...
;     for (int j = 0; j < 8; ++j) {
;         if (j < 6) gload(j + 2);
;         const LAS bf16* base = (const LAS bf16*)(lds + (j & 1) * STG);
;         if (j < 4) {
; #pragma unroll
;             for (int rt = 0; rt < 4; ++rt)
; #pragma unroll
;                 for (int kk = 0; kk < 8; ++kk) S[4 * j + rt] = mfma16(*(const LAS bf16x8*)(base + (16 * rt + fr) * KS + 32 * kk + 8 * fq), qf[kk], S[4 * j + rt]);
;             if (j == 3) {
;                 float mx = -3.0e38f;
; #pragma unroll
;                 for (int i = 0; i < 16; ++i) mx = fmaxf(mx, fmaxf(fmaxf(S[i][0], S[i][1]), fmaxf(S[i][2], S[i][3])));
;                 mx = fmaxf(mx, __shfl_xor(mx, 16)); mx = fmaxf(mx, __shfl_xor(mx, 32));
; #pragma unroll
;                 for (int i = 0; i < 16; ++i)
; #pragma unroll
;                     for (int k = 0; k < 4; ++k) { S[i][k] = __builtin_amdgcn_exp2f(S[i][k] - mx); l += S[i][k]; }
;                 l += __shfl_xor(l, 16); l += __shfl_xor(l, 32);
; #pragma unroll
;                 for (int c2 = 0; c2 < 8; ++c2) pf[c2] = pack8(S[2 * c2], S[2 * c2 + 1]);
;             }
;         } else {
;             const int mt = j - 4;
; #pragma unroll
;             for (int dt = 0; dt < 16; ++dt) {
;                 const LAS bf16* vr = base + (16 * dt + fr) * VS + 4 * fq;
;                 O[dt] = mfma16(cat8(*(const LAS u32x2*)vr, *(const LAS u32x2*)(vr + 16)), pf[2 * mt], O[dt]);
;                 O[dt] = mfma16(cat8(*(const LAS u32x2*)(vr + 32), *(const LAS u32x2*)(vr + 48)), pf[2 * mt + 1], O[dt]);
;             }
;         }
;         if (j < 7) lstore(j + 1);
;         __syncthreads();
	v_mfma_f32_16x16x32_bf16 v[182:185], v[152:155], v[112:115], v[184:187]
	ds_read_b128 v[152:155], v210 offset:53888
	ds_read_b128 v[196:199], v210 offset:53952
	v_add_u32_e32 v159, 0x2800, v156
	v_add_u32_e32 v157, 0x3000, v156
	s_waitcnt lgkmcnt(1)
	v_mfma_f32_16x16x32_bf16 v[186:189], v[152:155], v[112:115], v[188:191]
	ds_read_b128 v[152:155], v209 offset:36992
	ds_read_b128 v[214:217], v209 offset:37056
	v_add_u32_e32 v163, 0x800, v156
	s_waitcnt lgkmcnt(1)
	v_mfma_f32_16x16x32_bf16 v[218:221], v[152:155], v[112:115], v[120:123]
	v_mad_u32_u24 v152, v222, s22, v162
	v_add_u32_e32 v162, 0x1000, v156
	v_add_u32_e32 v154, 0x4800, v156
	v_mfma_f32_16x16x32_bf16 v[228:231], v[124:127], v[28:31], v[132:135]
	v_add_u32_e32 v155, 0x5000, v156
	v_add_u32_e32 v153, 0x5800, v156
	v_mfma_f32_16x16x32_bf16 v[132:135], v[136:139], v[28:31], v[164:167]
	v_add_u32_e32 v139, 0x6800, v156
	v_lshl_add_u64 v[136:137], s[4:5], 0, v[202:203]
	v_add_u32_e32 v138, 0x9000, v156
	v_mfma_f32_16x16x32_bf16 v[112:115], v[144:147], v[28:31], v[168:171]
	v_add_u32_e32 v146, 0x7000, v156
	v_add_u32_e32 v144, 0x7800, v156
	v_add_u32_e32 v145, 0x9800, v156
	v_mfma_f32_16x16x32_bf16 v[140:143], v[128:131], v[28:31], v[140:143]
	v_add_u32_e32 v147, 0xa000, v156
	v_add_u32_e32 v164, 0x9000, v151
	v_add_u32_e32 v165, 0xb000, v156
	v_mfma_f32_16x16x32_bf16 v[120:123], v[178:181], v[104:107], v[172:175]
	v_add_u32_e32 v166, 0xb800, v156
	v_add_u32_e32 v167, 0xc000, v156
	v_add_u32_e32 v168, 0x9000, v152
	v_mfma_f32_16x16x32_bf16 v[100:103], v[100:103], v[8:11], v[132:135]
	v_add_u32_e32 v169, 0xd800, v156
	v_add_u32_e32 v170, 0xe000, v156
	v_add_u32_e32 v171, 0xe800, v156
	v_mfma_f32_16x16x32_bf16 v[96:99], v[96:99], v[8:11], v[112:115]
	s_nop 2
	ds_read_b128 v[112:115], v210 offset:37120
	ds_read_b128 v[132:135], v210 offset:37184
	v_add_u32_e32 v172, 0x9000, v150
	v_add_u32_e32 v173, 0xf800, v156
	v_mfma_f32_16x16x32_bf16 v[124:127], v[192:195], v[104:107], v[182:185]
	v_add_u32_e32 v177, 0x7000, v138
	v_add_u32_e32 v175, 0x7800, v138
	v_add_u32_e32 v174, 0x9000, v149
	v_mfma_f32_16x16x32_bf16 v[108:111], v[108:111], v[8:11], v[140:143]
	v_lshl_add_u64 v[136:137], v[136:137], 0, s[0:1]
	v_lshl_add_u64 v[136:137], v[136:137], 0, v[200:201]
	s_waitcnt lgkmcnt(1)
	v_mfma_f32_16x16x32_bf16 v[112:115], v[112:115], v[28:31], v[120:123]
	s_nop 2
	ds_read_b128 v[120:123], v210 offset:45568
	ds_read_b128 v[140:143], v210 offset:45632
	v_mfma_f32_16x16x32_bf16 v[128:131], v[196:199], v[104:107], v[186:189]
	s_waitcnt lgkmcnt(1)
	v_mfma_f32_16x16x32_bf16 v[120:123], v[120:123], v[28:31], v[124:127]
	s_nop 2
	ds_read_b128 v[124:127], v210 offset:54016
	ds_read_b128 v[178:181], v210 offset:54080
	v_mfma_f32_16x16x32_bf16 v[104:107], v[214:217], v[104:107], v[218:221]
	s_waitcnt lgkmcnt(1)
	v_mfma_f32_16x16x32_bf16 v[124:127], v[124:127], v[28:31], v[128:131]
	s_nop 2
	ds_read_b128 v[128:131], v209 offset:37120
	ds_read_b128 v[182:185], v209 offset:37184
	v_mfma_f32_16x16x32_bf16 v[116:119], v[116:119], v[8:11], v[228:231]
	s_waitcnt lgkmcnt(1)
	v_mfma_f32_16x16x32_bf16 v[28:31], v[128:131], v[28:31], v[104:107]
	s_nop 2
	v_max_f32_e32 v104, v47, v47
	v_max_f32_e32 v105, v46, v46
	v_max_f32_e32 v106, v43, v43
	v_max_f32_e32 v107, v42, v42
	v_mfma_f32_16x16x32_bf16 v[72:75], v[72:75], v[4:7], v[116:119]
	v_max_f32_e32 v104, v105, v104
	s_nop 1
	v_max_f32_e32 v116, v39, v39
	v_max_f32_e32 v117, v38, v38
	v_mfma_f32_16x16x32_bf16 v[80:83], v[80:83], v[4:7], v[108:111]
	s_nop 2
	v_max_f32_e32 v108, v35, v35
	v_max_f32_e32 v109, v34, v34
	v_mfma_f32_16x16x32_bf16 v[88:91], v[88:91], v[4:7], v[100:103]
	s_nop 2
	v_max_f32_e32 v100, v107, v106
	v_max_f32_e32 v101, v117, v116
	v_max_f32_e32 v102, v109, v108
	v_max3_f32 v103, v44, v45, v104
	v_max3_f32 v100, v40, v41, v100
	v_mfma_f32_16x16x32_bf16 v[92:95], v[92:95], v[4:7], v[96:99]
	v_max3_f32 v101, v36, v37, v101
	v_max3_f32 v102, v32, v33, v102
	v_max3_f32 v100, v103, s21, v100
	v_mfma_f32_16x16x32_bf16 v[96:99], v[132:135], v[8:11], v[112:115]
	v_max_f32_e32 v108, v55, v55
	v_max_f32_e32 v109, v54, v54
	v_max_f32_e32 v116, v62, v62
	v_max_f32_e32 v113, v59, v59
	v_max_f32_e32 v114, v58, v58
	v_max3_f32 v112, v100, v101, v102
	v_mfma_f32_16x16x32_bf16 v[100:103], v[140:143], v[8:11], v[120:123]
	v_max_f32_e32 v115, v63, v63
	v_mfma_f32_16x16x32_bf16 v[104:107], v[178:181], v[8:11], v[124:127]
	s_waitcnt lgkmcnt(0)
	v_mfma_f32_16x16x32_bf16 v[8:11], v[182:185], v[8:11], v[28:31]
	s_nop 2
	v_max_f32_e32 v28, v51, v51
	v_max_f32_e32 v29, v50, v50
	v_max_f32_e32 v30, v109, v108
	v_max_f32_e32 v31, v114, v113
	v_mfma_f32_16x16x32_bf16 v[108:111], v[64:67], v[0:3], v[72:75]
	v_max_f32_e32 v64, v116, v115
	v_max_f32_e32 v28, v29, v28
	v_max3_f32 v29, v52, v53, v30
	v_max3_f32 v30, v56, v57, v31
	v_max3_f32 v31, v60, v61, v64
	v_max3_f32 v28, v48, v49, v28
	v_max3_f32 v29, v112, v29, v30
	v_max3_f32 v116, v29, v31, v28
	ds_read_b128 v[28:31], v210 offset:37248
	ds_read_b128 v[72:75], v210 offset:37312
	v_mfma_f32_16x16x32_bf16 v[76:79], v[76:79], v[0:3], v[88:91]
	v_max_f32_e32 v117, v111, v111
	v_max_f32_e32 v118, v110, v110
	v_mfma_f32_16x16x32_bf16 v[84:87], v[84:87], v[0:3], v[92:95]
	s_waitcnt lgkmcnt(1)
	v_mfma_f32_16x16x32_bf16 v[88:91], v[28:31], v[4:7], v[96:99]
	ds_read_b128 v[28:31], v210 offset:45696
	ds_read_b128 v[92:95], v210 offset:45760
	s_waitcnt lgkmcnt(1)
	v_mfma_f32_16x16x32_bf16 v[96:99], v[28:31], v[4:7], v[100:103]
	ds_read_b128 v[28:31], v210 offset:54144
	s_nop 1
	ds_read_b128 v[100:103], v210 offset:54208
	s_waitcnt lgkmcnt(1)
	v_mfma_f32_16x16x32_bf16 v[104:107], v[28:31], v[4:7], v[104:107]
	ds_read_b128 v[28:31], v209 offset:37248
	ds_read_b128 v[112:115], v209 offset:37312
	v_mfma_f32_16x16x32_bf16 v[80:83], v[68:71], v[0:3], v[80:83]
	s_waitcnt lgkmcnt(1)
	v_mfma_f32_16x16x32_bf16 v[4:7], v[28:31], v[4:7], v[8:11]
	global_load_dwordx4 v[68:71], v205, s[6:7] offset:128
	global_load_dwordx4 v[28:31], v206, s[6:7] offset:128
	global_load_dwordx4 v[64:67], v207, s[6:7] offset:128
	v_mfma_f32_16x16x32_bf16 v[8:11], v[72:75], v[0:3], v[88:91]
	global_load_dwordx4 v[72:75], v208, s[6:7] offset:128
	s_waitcnt vmcnt(7)
	ds_write_b128 v176, v[12:15]
	s_waitcnt vmcnt(6)
	ds_write_b128 v160, v[16:19]
	s_waitcnt vmcnt(5)
	ds_write_b128 v161, v[20:23]
	s_waitcnt vmcnt(4)
	ds_write_b128 v148, v[24:27]
	s_waitcnt lgkmcnt(0)
	v_mfma_f32_16x16x32_bf16 v[88:91], v[92:95], v[0:3], v[96:99]
	s_barrier
; #define LAS __attribute__((address_space(3)))
; __device__ __forceinline__ f32x4 mfma16(bf16x8 a, bf16x8 b, f32x4 c) { return __builtin_amdgcn_mfma_f32_16x16x32_bf16(a, b, c, 0, 0, 0); }
; __device__ __forceinline__ bf16x8 pack8(f32x4 a, f32x4 b) { u32x4 w; w.x = pk2(a[0], a[1]); w.y = pk2(a[2], a[3]); w.z = pk2(b[0], b[1]); w.w = pk2(b[2], b[3]); return __builtin_bit_cast(bf16x8, w); }
; __device__ __forceinline__ void xattn_unit(const Args& a, LAS unsigned char* lds, int b, int h, int qb, int tid, int wave, int lane) {
;     ...
;             if (j == 3) {
;                 float mx = -3.0e38f;
; #pragma unroll
;                 for (int i = 0; i < 16; ++i) mx = fmaxf(mx, fmaxf(fmaxf(S[i][0], S[i][1]), fmaxf(S[i][2], S[i][3])));
;                 mx = fmaxf(mx, __shfl_xor(mx, 16)); mx = fmaxf(mx, __shfl_xor(mx, 32));
; #pragma unroll
;                 for (int i = 0; i < 16; ++i)
; #pragma unroll
;                     for (int k = 0; k < 4; ++k) { S[i][k] = __builtin_amdgcn_exp2f(S[i][k] - mx); l += S[i][k]; }
;                 l += __shfl_xor(l, 16); l += __shfl_xor(l, 32);
; #pragma unroll
;                 for (int c2 = 0; c2 < 8; ++c2) pf[c2] = pack8(S[2 * c2], S[2 * c2 + 1]);
;             }
;         } else {
;             const int mt = j - 4;
; #pragma unroll
;             for (int dt = 0; dt < 16; ++dt) {
;                 const LAS bf16* vr = base + (16 * dt + fr) * VS + 4 * fq;
;                 O[dt] = mfma16(cat8(*(const LAS u32x2*)vr, *(const LAS u32x2*)(vr + 16)), pf[2 * mt], O[dt]);
;                 O[dt] = mfma16(cat8(*(const LAS u32x2*)(vr + 32), *(const LAS u32x2*)(vr + 48)), pf[2 * mt + 1], O[dt]);
;             }
	ds_read2_b64 v[12:15], v156 offset1:4
	ds_read2_b64 v[16:19], v163 offset0:32 offset1:36
	v_max_f32_e32 v96, v83, v83
	v_max_f32_e32 v97, v82, v82
	v_max_f32_e32 v98, v79, v79
	v_mfma_f32_16x16x32_bf16 v[92:95], v[100:103], v[0:3], v[104:107]
	v_max_f32_e32 v99, v78, v78
	v_max_f32_e32 v100, v87, v87
	v_max_f32_e32 v101, v86, v86
	v_mfma_f32_16x16x32_bf16 v[0:3], v[112:115], v[0:3], v[4:7]
	ds_read2_b64 v[20:23], v162 offset0:64 offset1:68
	ds_read2_b64 v[24:27], v151 offset1:4
	ds_read2_b64 v[112:115], v156 offset0:8 offset1:12
	v_max_f32_e32 v4, v118, v117
	v_max_f32_e32 v5, v97, v96
	v_max_f32_e32 v6, v99, v98
	v_max_f32_e32 v7, v101, v100
	v_max3_f32 v4, v108, v109, v4
	v_max3_f32 v5, v80, v81, v5
	v_max3_f32 v6, v76, v77, v6
	v_max3_f32 v7, v84, v85, v7
	v_max3_f32 v4, v116, v4, v5
	v_max3_f32 v4, v4, v6, v7
	v_max_f32_e32 v5, v11, v11
	v_max_f32_e32 v6, v10, v10
	v_max_f32_e32 v7, v91, v91
	v_max_f32_e32 v96, v90, v90
	v_max_f32_e32 v97, v95, v95
	v_max_f32_e32 v98, v94, v94
	v_max_f32_e32 v99, v3, v3
	v_max_f32_e32 v100, v2, v2
	v_max_f32_e32 v5, v6, v5
	v_max_f32_e32 v6, v96, v7
	v_max_f32_e32 v7, v98, v97
	v_max_f32_e32 v96, v100, v99
	v_max3_f32 v5, v8, v9, v5
	v_max3_f32 v6, v88, v89, v6
	v_max3_f32 v7, v92, v93, v7
	v_max3_f32 v96, v0, v1, v96
	v_max3_f32 v4, v4, v5, v6
	v_max3_f32 v4, v4, v7, v96
	ds_bpermute_b32 v5, v211, v4
	s_waitcnt lgkmcnt(0)
	v_max_f32_e32 v5, v5, v5
	v_max_f32_e32 v4, v4, v5
	ds_bpermute_b32 v5, v212, v4
	s_waitcnt lgkmcnt(0)
	v_max_f32_e32 v5, v5, v5
	v_max_f32_e32 v4, v4, v5
	v_sub_f32_e32 v5, v44, v4
	v_sub_f32_e32 v6, v45, v4
	v_sub_f32_e32 v7, v46, v4
	v_sub_f32_e32 v44, v47, v4
	v_sub_f32_e32 v40, v40, v4
	v_sub_f32_e32 v41, v41, v4
	v_sub_f32_e32 v42, v42, v4
	v_sub_f32_e32 v43, v43, v4
	v_sub_f32_e32 v36, v36, v4
	v_sub_f32_e32 v37, v37, v4
	v_sub_f32_e32 v38, v38, v4
	v_sub_f32_e32 v39, v39, v4
	v_sub_f32_e32 v32, v32, v4
	v_sub_f32_e32 v33, v33, v4
	v_sub_f32_e32 v34, v34, v4
	v_sub_f32_e32 v35, v35, v4
	v_sub_f32_e32 v45, v52, v4
	v_sub_f32_e32 v46, v53, v4
	v_sub_f32_e32 v47, v54, v4
	v_sub_f32_e32 v52, v55, v4
	v_sub_f32_e32 v53, v56, v4
	v_sub_f32_e32 v54, v57, v4
	v_sub_f32_e32 v55, v58, v4
	v_sub_f32_e32 v56, v59, v4
	v_sub_f32_e32 v57, v60, v4
	v_sub_f32_e32 v58, v61, v4
	v_sub_f32_e32 v59, v62, v4
	v_sub_f32_e32 v60, v63, v4
	v_sub_f32_e32 v48, v48, v4
	v_sub_f32_e32 v49, v49, v4
	v_sub_f32_e32 v50, v50, v4
	v_sub_f32_e32 v51, v51, v4
	v_sub_f32_e32 v61, v108, v4
	v_sub_f32_e32 v62, v109, v4
	v_sub_f32_e32 v63, v110, v4
	v_sub_f32_e32 v96, v111, v4
	v_sub_f32_e32 v80, v80, v4
	v_sub_f32_e32 v81, v81, v4
	v_sub_f32_e32 v82, v82, v4
	v_sub_f32_e32 v83, v83, v4
	v_sub_f32_e32 v76, v76, v4
	v_sub_f32_e32 v77, v77, v4
	v_sub_f32_e32 v78, v78, v4
	v_sub_f32_e32 v79, v79, v4
	v_sub_f32_e32 v84, v84, v4
	v_sub_f32_e32 v85, v85, v4
	v_sub_f32_e32 v86, v86, v4
	v_sub_f32_e32 v87, v87, v4
	v_sub_f32_e32 v8, v8, v4
	v_sub_f32_e32 v9, v9, v4
	v_sub_f32_e32 v10, v10, v4
	v_sub_f32_e32 v11, v11, v4
	v_sub_f32_e32 v88, v88, v4
	v_sub_f32_e32 v89, v89, v4
	v_sub_f32_e32 v90, v90, v4
	v_sub_f32_e32 v91, v91, v4
	v_sub_f32_e32 v92, v92, v4
	v_sub_f32_e32 v93, v93, v4
	v_sub_f32_e32 v94, v94, v4
	v_sub_f32_e32 v95, v95, v4
	v_sub_f32_e32 v0, v0, v4
	v_sub_f32_e32 v1, v1, v4
	v_sub_f32_e32 v2, v2, v4
	v_sub_f32_e32 v3, v3, v4
	v_exp_f32_e32 v4, v5
	v_exp_f32_e32 v97, v6
	v_exp_f32_e32 v98, v7
	v_exp_f32_e32 v99, v44
	v_exp_f32_e32 v100, v40
	v_exp_f32_e32 v189, v52
	v_add_f32_e32 v52, 0, v4
	v_exp_f32_e32 v101, v41
	v_add_f32_e32 v52, v97, v52
	v_exp_f32_e32 v102, v42
	v_add_f32_e32 v52, v98, v52
	v_exp_f32_e32 v103, v43
	v_add_f32_e32 v52, v99, v52
	v_exp_f32_e32 v104, v36
	v_add_f32_e32 v52, v100, v52
	v_exp_f32_e32 v105, v37
	v_add_f32_e32 v52, v101, v52
	v_exp_f32_e32 v106, v38
	v_exp_f32_e32 v120, v39
	v_add_f32_e32 v52, v102, v52
	v_add_f32_e32 v52, v103, v52
	v_add_f32_e32 v52, v104, v52
	v_add_f32_e32 v52, v105, v52
	v_exp_f32_e32 v190, v53
	v_exp_f32_e32 v191, v54
	v_exp_f32_e32 v192, v55
	v_exp_f32_e32 v193, v56
	v_exp_f32_e32 v194, v57
	v_exp_f32_e32 v195, v58
	v_exp_f32_e32 v196, v59
	v_exp_f32_e32 v197, v60
	v_exp_f32_e32 v203, v61
	v_exp_f32_e32 v209, v62
	v_exp_f32_e32 v210, v63
	v_exp_f32_e32 v213, v96
	v_exp_f32_e32 v214, v80
	v_exp_f32_e32 v215, v81
	v_exp_f32_e32 v216, v82
	v_exp_f32_e32 v217, v83
	v_exp_f32_e32 v218, v76
	v_exp_f32_e32 v219, v77
	v_exp_f32_e32 v220, v78
	v_exp_f32_e32 v221, v79
	v_exp_f32_e32 v222, v84
	v_exp_f32_e32 v223, v85
	v_exp_f32_e32 v224, v86
	v_exp_f32_e32 v225, v87
	v_exp_f32_e32 v232, v88
	v_exp_f32_e32 v233, v89
	v_exp_f32_e32 v234, v90
	v_exp_f32_e32 v235, v91
	v_exp_f32_e32 v236, v92
	v_exp_f32_e32 v237, v93
	v_exp_f32_e32 v238, v94
	v_exp_f32_e32 v239, v95
	v_cvt_pk_bf16_f32 v36, v4, v97
	v_cvt_pk_bf16_f32 v37, v98, v99
	v_cvt_pk_bf16_f32 v38, v100, v101
	v_cvt_pk_bf16_f32 v39, v102, v103
	v_cvt_pk_bf16_f32 v40, v104, v105
	v_cvt_pk_bf16_f32 v41, v106, v120
	v_add_f32_e32 v121, v106, v52
	ds_read2_b64 v[52:55], v158 offset0:128 offset1:132
	ds_read2_b64 v[56:59], v159 offset0:160 offset1:164
	ds_read2_b64 v[60:63], v157 offset0:192 offset1:196
	ds_read2_b64 v[76:79], v152 offset1:4
	ds_read2_b64 v[80:83], v154 offset1:4
	ds_read2_b64 v[84:87], v155 offset0:32 offset1:36
	ds_read2_b64 v[88:91], v153 offset0:64 offset1:68
	ds_read2_b64 v[92:95], v150 offset1:4
	ds_read2_b64 v[96:99], v139 offset0:128 offset1:132
	ds_read2_b64 v[100:103], v146 offset0:160 offset1:164
	ds_read2_b64 v[104:107], v144 offset0:192 offset1:196
	ds_read2_b64 v[108:111], v149 offset1:4
	v_exp_f32_e32 v182, v32
	v_exp_f32_e32 v183, v33
	v_exp_f32_e32 v184, v34
	v_exp_f32_e32 v185, v35
	v_mfma_f32_16x16x32_bf16 v[12:15], v[12:15], v[36:39], 0
	v_cvt_pk_bf16_f32 v42, v182, v183
	v_add_f32_e32 v244, v120, v121
	v_cvt_pk_bf16_f32 v43, v184, v185
	v_mfma_f32_16x16x32_bf16 v[16:19], v[16:19], v[36:39], 0
	v_exp_f32_e32 v186, v45
	v_exp_f32_e32 v187, v46
	v_exp_f32_e32 v188, v47
	v_mfma_f32_16x16x32_bf16 v[20:23], v[20:23], v[36:39], 0
	v_cvt_pk_bf16_f32 v46, v190, v191
	v_cvt_pk_bf16_f32 v44, v186, v187
	v_cvt_pk_bf16_f32 v45, v188, v189
	v_mfma_f32_16x16x32_bf16 v[24:27], v[24:27], v[36:39], 0
	v_cvt_pk_bf16_f32 v47, v192, v193
	v_exp_f32_e32 v198, v48
	v_exp_f32_e32 v199, v49
	s_waitcnt lgkmcnt(11)
; #define LAS __attribute__((address_space(3)))
; __device__ __forceinline__ f32x4 mfma16(bf16x8 a, bf16x8 b, f32x4 c) { return __builtin_amdgcn_mfma_f32_16x16x32_bf16(a, b, c, 0, 0, 0); }
; __device__ __forceinline__ void xattn_unit(const Args& a, LAS unsigned char* lds, int b, int h, int qb, int tid, int wave, int lane) {
;     ...
;         } else {
;             const int mt = j - 4;
; #pragma unroll
;             for (int dt = 0; dt < 16; ++dt) {
;                 const LAS bf16* vr = base + (16 * dt + fr) * VS + 4 * fq;
;                 O[dt] = mfma16(cat8(*(const LAS u32x2*)vr, *(const LAS u32x2*)(vr + 16)), pf[2 * mt], O[dt]);
;                 O[dt] = mfma16(cat8(*(const LAS u32x2*)(vr + 32), *(const LAS u32x2*)(vr + 48)), pf[2 * mt + 1], O[dt]);
;             }
;         }
;         if (j < 7) lstore(j + 1);
;         __syncthreads();
;     }
	v_mfma_f32_16x16x32_bf16 v[52:55], v[52:55], v[36:39], 0
	v_exp_f32_e32 v200, v50
	v_exp_f32_e32 v202, v51
	v_cvt_pk_bf16_f32 v48, v194, v195
	s_waitcnt lgkmcnt(10)
	v_mfma_f32_16x16x32_bf16 v[56:59], v[56:59], v[36:39], 0
	v_cvt_pk_bf16_f32 v49, v196, v197
	v_cvt_pk_bf16_f32 v50, v198, v199
	v_cvt_pk_bf16_f32 v51, v200, v202
	s_waitcnt lgkmcnt(9)
	v_mfma_f32_16x16x32_bf16 v[60:63], v[60:63], v[36:39], 0
	v_add_f32_e32 v182, v182, v244
	v_exp_f32_e32 v228, v8
	v_exp_f32_e32 v229, v9
	s_waitcnt lgkmcnt(8)
	v_mfma_f32_16x16x32_bf16 v[76:79], v[76:79], v[36:39], 0
	v_exp_f32_e32 v230, v10
	v_exp_f32_e32 v231, v11
	v_exp_f32_e32 v240, v0
	s_waitcnt lgkmcnt(7)
	v_mfma_f32_16x16x32_bf16 v[80:83], v[80:83], v[36:39], 0
	v_exp_f32_e32 v241, v1
	v_exp_f32_e32 v242, v2
	v_exp_f32_e32 v243, v3
	s_waitcnt lgkmcnt(6)
	v_mfma_f32_16x16x32_bf16 v[84:87], v[84:87], v[36:39], 0
	v_cvt_pk_bf16_f32 v32, v203, v209
	v_cvt_pk_bf16_f32 v33, v210, v213
	v_cvt_pk_bf16_f32 v34, v214, v215
	s_waitcnt lgkmcnt(5)
	v_mfma_f32_16x16x32_bf16 v[88:91], v[88:91], v[36:39], 0
	v_cvt_pk_bf16_f32 v35, v216, v217
	v_cvt_pk_bf16_f32 v8, v218, v219
	v_cvt_pk_bf16_f32 v9, v220, v221
	s_waitcnt lgkmcnt(4)
	v_mfma_f32_16x16x32_bf16 v[92:95], v[92:95], v[36:39], 0
	v_cvt_pk_bf16_f32 v10, v222, v223
	v_cvt_pk_bf16_f32 v11, v224, v225
	v_cvt_pk_bf16_f32 v4, v228, v229
	s_waitcnt lgkmcnt(3)
	v_mfma_f32_16x16x32_bf16 v[96:99], v[96:99], v[36:39], 0
	v_cvt_pk_bf16_f32 v5, v230, v231
	v_cvt_pk_bf16_f32 v6, v232, v233
	v_cvt_pk_bf16_f32 v7, v234, v235
	s_waitcnt lgkmcnt(2)
	v_mfma_f32_16x16x32_bf16 v[100:103], v[100:103], v[36:39], 0
	v_cvt_pk_bf16_f32 v0, v236, v237
	v_cvt_pk_bf16_f32 v1, v238, v239
	v_cvt_pk_bf16_f32 v2, v240, v241
	s_waitcnt lgkmcnt(1)
	v_mfma_f32_16x16x32_bf16 v[104:107], v[104:107], v[36:39], 0
	v_cvt_pk_bf16_f32 v3, v242, v243
	s_waitcnt lgkmcnt(0)
	v_mfma_f32_16x16x32_bf16 v[36:39], v[108:111], v[36:39], 0
	ds_read2_b64 v[108:111], v163 offset0:40 offset1:44
	v_mfma_f32_16x16x32_bf16 v[12:15], v[112:115], v[40:43], v[12:15]
	ds_read2_b64 v[112:115], v162 offset0:72 offset1:76
	s_waitcnt lgkmcnt(1)
	v_mfma_f32_16x16x32_bf16 v[16:19], v[108:111], v[40:43], v[16:19]
	ds_read2_b64 v[108:111], v151 offset0:8 offset1:12
	s_waitcnt lgkmcnt(1)
	v_mfma_f32_16x16x32_bf16 v[20:23], v[112:115], v[40:43], v[20:23]
	ds_read2_b64 v[112:115], v158 offset0:136 offset1:140
	s_waitcnt lgkmcnt(1)
	v_mfma_f32_16x16x32_bf16 v[24:27], v[108:111], v[40:43], v[24:27]
	ds_read2_b64 v[108:111], v159 offset0:168 offset1:172
	s_waitcnt lgkmcnt(1)
	v_mfma_f32_16x16x32_bf16 v[52:55], v[112:115], v[40:43], v[52:55]
	ds_read2_b64 v[112:115], v157 offset0:200 offset1:204
	s_waitcnt lgkmcnt(1)
	v_mfma_f32_16x16x32_bf16 v[56:59], v[108:111], v[40:43], v[56:59]
	ds_read2_b64 v[108:111], v152 offset0:8 offset1:12
	s_waitcnt lgkmcnt(1)
	v_mfma_f32_16x16x32_bf16 v[60:63], v[112:115], v[40:43], v[60:63]
	ds_read2_b64 v[112:115], v154 offset0:8 offset1:12
	ds_read2_b64 v[116:119], v155 offset0:40 offset1:44
	ds_read2_b64 v[120:123], v153 offset0:72 offset1:76
	s_waitcnt lgkmcnt(3)
	v_mfma_f32_16x16x32_bf16 v[76:79], v[108:111], v[40:43], v[76:79]
	global_load_dwordx4 v[108:111], v205, s[6:7] offset:256
	s_waitcnt lgkmcnt(2)
	v_mfma_f32_16x16x32_bf16 v[80:83], v[112:115], v[40:43], v[80:83]
	global_load_dwordx4 v[112:115], v206, s[6:7] offset:256
	global_load_dwordx4 v[124:127], v207, s[6:7] offset:256
	ds_read2_b64 v[128:131], v150 offset0:8 offset1:12
	s_waitcnt lgkmcnt(2)
	v_mfma_f32_16x16x32_bf16 v[84:87], v[116:119], v[40:43], v[84:87]
	global_load_dwordx4 v[116:119], v208, s[6:7] offset:256
	ds_read2_b64 v[132:135], v139 offset0:136 offset1:140
	ds_read2_b64 v[140:143], v146 offset0:168 offset1:172
	s_waitcnt lgkmcnt(3)
	v_mfma_f32_16x16x32_bf16 v[88:91], v[120:123], v[40:43], v[88:91]
	ds_read2_b64 v[120:123], v144 offset0:200 offset1:204
	ds_read2_b64 v[178:181], v149 offset0:8 offset1:12
	s_waitcnt vmcnt(7)
	ds_write_b128 v176, v[68:71] offset:36864
	s_waitcnt vmcnt(6)
	ds_write_b128 v160, v[28:31] offset:36864
	s_waitcnt vmcnt(5)
	ds_write_b128 v161, v[64:67] offset:36864
	s_waitcnt vmcnt(4)
	ds_write_b128 v148, v[72:75] offset:36864
	s_waitcnt lgkmcnt(0)
	s_barrier
	ds_read2_b64 v[72:75], v138 offset1:4
	v_mfma_f32_16x16x32_bf16 v[92:95], v[128:131], v[40:43], v[92:95]
	v_add_f32_e32 v128, v183, v182
	v_add_f32_e32 v128, v184, v128
	v_mfma_f32_16x16x32_bf16 v[68:71], v[132:135], v[40:43], v[96:99]
	v_mfma_f32_16x16x32_bf16 v[28:31], v[140:143], v[40:43], v[100:103]
	v_mfma_f32_16x16x32_bf16 v[64:67], v[120:123], v[40:43], v[104:107]
	v_mfma_f32_16x16x32_bf16 v[36:39], v[178:181], v[40:43], v[36:39]
	ds_read2_b64 v[40:43], v145 offset0:32 offset1:36
	v_add_f32_e32 v178, v185, v128
	v_add_f32_e32 v178, v186, v178
	s_waitcnt lgkmcnt(1)
	v_mfma_f32_16x16x32_bf16 v[12:15], v[72:75], v[44:47], v[12:15]
	ds_read2_b64 v[72:75], v147 offset0:64 offset1:68
	v_add_f32_e32 v178, v187, v178
	s_waitcnt lgkmcnt(1)
	v_mfma_f32_16x16x32_bf16 v[16:19], v[40:43], v[44:47], v[16:19]
	ds_read2_b64 v[40:43], v164 offset1:4
	s_waitcnt lgkmcnt(1)
	v_mfma_f32_16x16x32_bf16 v[20:23], v[72:75], v[44:47], v[20:23]
	ds_read2_b64 v[72:75], v165 offset0:128 offset1:132
	s_waitcnt lgkmcnt(1)
	v_mfma_f32_16x16x32_bf16 v[24:27], v[40:43], v[44:47], v[24:27]
	ds_read2_b64 v[40:43], v166 offset0:160 offset1:164
	s_waitcnt lgkmcnt(1)
	v_mfma_f32_16x16x32_bf16 v[52:55], v[72:75], v[44:47], v[52:55]
	ds_read2_b64 v[72:75], v167 offset0:192 offset1:196
	s_waitcnt lgkmcnt(1)
	v_mfma_f32_16x16x32_bf16 v[40:43], v[40:43], v[44:47], v[56:59]
	s_nop 2
	ds_read2_b64 v[56:59], v168 offset1:4
	s_waitcnt lgkmcnt(1)
; #define LAS __attribute__((address_space(3)))
; __device__ __forceinline__ f32x4 mfma16(bf16x8 a, bf16x8 b, f32x4 c) { return __builtin_amdgcn_mfma_f32_16x16x32_bf16(a, b, c, 0, 0, 0); }
; __device__ __forceinline__ bf16x8 pack8(f32x4 a, f32x4 b) { u32x4 w; w.x = pk2(a[0], a[1]); w.y = pk2(a[2], a[3]); w.z = pk2(b[0], b[1]); w.w = pk2(b[2], b[3]); return __builtin_bit_cast(bf16x8, w); }
; __device__ __forceinline__ void xattn_unit(const Args& a, LAS unsigned char* lds, int b, int h, int qb, int tid, int wave, int lane) {
;     ...
;                 l += __shfl_xor(l, 16); l += __shfl_xor(l, 32);
; #pragma unroll
;                 for (int c2 = 0; c2 < 8; ++c2) pf[c2] = pack8(S[2 * c2], S[2 * c2 + 1]);
;             }
;         } else {
;             const int mt = j - 4;
; #pragma unroll
;             for (int dt = 0; dt < 16; ++dt) {
;                 const LAS bf16* vr = base + (16 * dt + fr) * VS + 4 * fq;
;                 O[dt] = mfma16(cat8(*(const LAS u32x2*)vr, *(const LAS u32x2*)(vr + 16)), pf[2 * mt], O[dt]);
;                 O[dt] = mfma16(cat8(*(const LAS u32x2*)(vr + 32), *(const LAS u32x2*)(vr + 48)), pf[2 * mt + 1], O[dt]);
;             }
;         }
;         if (j < 7) lstore(j + 1);
;         __syncthreads();
;     }
;     const float il = 1.f / l;
	v_mfma_f32_16x16x32_bf16 v[60:63], v[72:75], v[44:47], v[60:63]
	ds_read2_b64 v[72:75], v169 offset1:4
	s_waitcnt lgkmcnt(1)
	v_mfma_f32_16x16x32_bf16 v[56:59], v[56:59], v[44:47], v[76:79]
	s_nop 2
	ds_read2_b64 v[76:79], v170 offset0:32 offset1:36
	s_waitcnt lgkmcnt(1)
	v_mfma_f32_16x16x32_bf16 v[72:75], v[72:75], v[44:47], v[80:83]
	s_nop 2
	ds_read2_b64 v[80:83], v171 offset0:64 offset1:68
	s_waitcnt lgkmcnt(1)
	v_mfma_f32_16x16x32_bf16 v[76:79], v[76:79], v[44:47], v[84:87]
	s_nop 2
	ds_read2_b64 v[84:87], v172 offset1:4
	s_waitcnt lgkmcnt(1)
	v_mfma_f32_16x16x32_bf16 v[80:83], v[80:83], v[44:47], v[88:91]
	s_nop 2
	ds_read2_b64 v[88:91], v173 offset0:128 offset1:132
	s_waitcnt lgkmcnt(1)
	v_mfma_f32_16x16x32_bf16 v[84:87], v[84:87], v[44:47], v[92:95]
	s_nop 2
	ds_read2_b64 v[92:95], v177 offset0:160 offset1:164
	s_waitcnt lgkmcnt(1)
	v_mfma_f32_16x16x32_bf16 v[68:71], v[88:91], v[44:47], v[68:71]
	ds_read2_b64 v[88:91], v175 offset0:192 offset1:196
	s_waitcnt lgkmcnt(1)
	v_mfma_f32_16x16x32_bf16 v[28:31], v[92:95], v[44:47], v[28:31]
	ds_read2_b64 v[92:95], v174 offset1:4
	s_waitcnt lgkmcnt(1)
	v_mfma_f32_16x16x32_bf16 v[64:67], v[88:91], v[44:47], v[64:67]
	ds_read2_b64 v[88:91], v138 offset0:8 offset1:12
	s_waitcnt lgkmcnt(1)
	v_mfma_f32_16x16x32_bf16 v[36:39], v[92:95], v[44:47], v[36:39]
	ds_read2_b64 v[44:47], v145 offset0:40 offset1:44
	s_waitcnt lgkmcnt(1)
	v_mfma_f32_16x16x32_bf16 v[12:15], v[88:91], v[48:51], v[12:15]
	ds_read2_b64 v[88:91], v147 offset0:72 offset1:76
	s_waitcnt lgkmcnt(1)
	v_mfma_f32_16x16x32_bf16 v[16:19], v[44:47], v[48:51], v[16:19]
	ds_read2_b64 v[44:47], v164 offset0:8 offset1:12
	s_waitcnt lgkmcnt(1)
	v_mfma_f32_16x16x32_bf16 v[20:23], v[88:91], v[48:51], v[20:23]
	ds_read2_b64 v[88:91], v165 offset0:136 offset1:140
	s_waitcnt lgkmcnt(1)
	v_mfma_f32_16x16x32_bf16 v[24:27], v[44:47], v[48:51], v[24:27]
	ds_read2_b64 v[44:47], v166 offset0:168 offset1:172
	s_waitcnt lgkmcnt(1)
	v_mfma_f32_16x16x32_bf16 v[52:55], v[88:91], v[48:51], v[52:55]
	ds_read2_b64 v[88:91], v167 offset0:200 offset1:204
	ds_read2_b64 v[92:95], v168 offset0:8 offset1:12
	ds_read2_b64 v[96:99], v169 offset0:8 offset1:12
	s_waitcnt lgkmcnt(3)
	v_mfma_f32_16x16x32_bf16 v[40:43], v[44:47], v[48:51], v[40:43]
	global_load_dwordx4 v[44:47], v205, s[6:7] offset:384
	s_waitcnt lgkmcnt(2)
	v_mfma_f32_16x16x32_bf16 v[60:63], v[88:91], v[48:51], v[60:63]
	global_load_dwordx4 v[88:91], v206, s[6:7] offset:384
	global_load_dwordx4 v[100:103], v207, s[6:7] offset:384
	ds_read2_b64 v[104:107], v170 offset0:40 offset1:44
	s_waitcnt lgkmcnt(2)
	v_mfma_f32_16x16x32_bf16 v[56:59], v[92:95], v[48:51], v[56:59]
	global_load_dwordx4 v[92:95], v208, s[6:7] offset:384
	ds_read2_b64 v[120:123], v171 offset0:72 offset1:76
	ds_read2_b64 v[128:131], v172 offset0:8 offset1:12
	s_waitcnt lgkmcnt(1)
	v_mfma_f32_16x16x32_bf16 v[80:83], v[120:123], v[48:51], v[80:83]
	v_add_f32_e32 v120, v188, v178
	v_add_f32_e32 v120, v189, v120
	v_add_f32_e32 v120, v190, v120
	v_mfma_f32_16x16x32_bf16 v[72:75], v[96:99], v[48:51], v[72:75]
	ds_read2_b64 v[96:99], v173 offset0:136 offset1:140
	ds_read2_b64 v[132:135], v177 offset0:168 offset1:172
	ds_read2_b64 v[140:143], v175 offset0:200 offset1:204
	v_add_f32_e32 v120, v191, v120
	v_add_f32_e32 v120, v192, v120
	v_add_f32_e32 v120, v193, v120
	v_mfma_f32_16x16x32_bf16 v[76:79], v[104:107], v[48:51], v[76:79]
	ds_read2_b64 v[104:107], v174 offset0:8 offset1:12
	s_waitcnt vmcnt(7)
	ds_write_b128 v176, v[108:111]
	s_waitcnt vmcnt(6)
	ds_write_b128 v160, v[112:115]
	s_waitcnt vmcnt(5)
	ds_write_b128 v161, v[124:127]
	s_waitcnt vmcnt(4)
	ds_write_b128 v148, v[116:119]
	s_waitcnt lgkmcnt(0)
	v_mfma_f32_16x16x32_bf16 v[68:71], v[96:99], v[48:51], v[68:71]
	v_add_f32_e32 v96, v194, v120
	v_add_f32_e32 v96, v195, v96
	v_add_f32_e32 v96, v196, v96
	v_add_f32_e32 v96, v197, v96
	v_add_f32_e32 v96, v198, v96
	v_add_f32_e32 v96, v199, v96
	v_add_f32_e32 v96, v200, v96
	v_add_f32_e32 v96, v202, v96
	v_add_f32_e32 v96, v203, v96
	v_mfma_f32_16x16x32_bf16 v[84:87], v[128:131], v[48:51], v[84:87]
	s_barrier
	v_mfma_f32_16x16x32_bf16 v[28:31], v[132:135], v[48:51], v[28:31]
	v_mfma_f32_16x16x32_bf16 v[64:67], v[140:143], v[48:51], v[64:67]
	v_mfma_f32_16x16x32_bf16 v[36:39], v[104:107], v[48:51], v[36:39]
	v_add_f32_e32 v48, v209, v96
	v_add_f32_e32 v48, v210, v48
	v_add_f32_e32 v48, v213, v48
	v_add_f32_e32 v48, v214, v48
	v_add_f32_e32 v48, v215, v48
	v_add_f32_e32 v48, v216, v48
	v_add_f32_e32 v48, v217, v48
	v_add_f32_e32 v48, v218, v48
	v_add_f32_e32 v48, v219, v48
	v_add_f32_e32 v48, v220, v48
	v_add_f32_e32 v48, v221, v48
	v_add_f32_e32 v48, v222, v48
	v_add_f32_e32 v48, v223, v48
	v_add_f32_e32 v48, v224, v48
	v_add_f32_e32 v48, v225, v48
	v_add_f32_e32 v48, v228, v48
	v_add_f32_e32 v48, v229, v48
	v_add_f32_e32 v48, v230, v48
	v_add_f32_e32 v48, v231, v48
	v_add_f32_e32 v48, v232, v48
	v_add_f32_e32 v48, v233, v48
	v_add_f32_e32 v48, v234, v48
	v_add_f32_e32 v48, v235, v48
	v_add_f32_e32 v48, v236, v48
	v_add_f32_e32 v48, v237, v48
	v_add_f32_e32 v48, v238, v48
	v_add_f32_e32 v48, v239, v48
	v_add_f32_e32 v48, v240, v48
	v_add_f32_e32 v48, v241, v48
	v_add_f32_e32 v48, v242, v48
	v_add_f32_e32 v48, v243, v48
	ds_bpermute_b32 v49, v211, v48
	s_waitcnt lgkmcnt(0)
	v_add_f32_e32 v48, v48, v49
	ds_bpermute_b32 v49, v212, v48
	s_waitcnt lgkmcnt(0)
	v_add_f32_e32 v48, v48, v49
	v_div_scale_f32 v49, s[6:7], v48, v48, 1.0
	v_rcp_f32_e32 v51, v49
	v_div_scale_f32 v50, vcc, 1.0, v48, 1.0
	v_fma_f32 v96, -v49, v51, 1.0
	v_fmac_f32_e32 v51, v96, v51
	v_mul_f32_e32 v96, v50, v51
	v_fma_f32 v97, -v49, v96, v50
	v_fmac_f32_e32 v96, v97, v51
	v_fma_f32 v49, -v49, v96, v50
	v_div_fmas_f32 v49, v49, v51, v96
	v_div_fixup_f32 v120, v49, v48, 1.0
	ds_read2_b64 v[48:51], v156 offset1:4
	ds_read2_b64 v[96:99], v163 offset0:32 offset1:36
	s_waitcnt lgkmcnt(1)
; #define LAS __attribute__((address_space(3)))
; __device__ __forceinline__ f32x4 mfma16(bf16x8 a, bf16x8 b, f32x4 c) { return __builtin_amdgcn_mfma_f32_16x16x32_bf16(a, b, c, 0, 0, 0); }
; __device__ __forceinline__ void xattn_unit(const Args& a, LAS unsigned char* lds, int b, int h, int qb, int tid, int wave, int lane) {
;     ...
;         } else {
;             const int mt = j - 4;
; #pragma unroll
;             for (int dt = 0; dt < 16; ++dt) {
;                 const LAS bf16* vr = base + (16 * dt + fr) * VS + 4 * fq;
;                 O[dt] = mfma16(cat8(*(const LAS u32x2*)vr, *(const LAS u32x2*)(vr + 16)), pf[2 * mt], O[dt]);
;                 O[dt] = mfma16(cat8(*(const LAS u32x2*)(vr + 32), *(const LAS u32x2*)(vr + 48)), pf[2 * mt + 1], O[dt]);
;             }
;         }
;         if (j < 7) lstore(j + 1);
;         __syncthreads();
;     }
	v_mfma_f32_16x16x32_bf16 v[12:15], v[48:51], v[32:35], v[12:15]
	ds_read2_b64 v[48:51], v162 offset0:64 offset1:68
	s_waitcnt lgkmcnt(1)
	v_mfma_f32_16x16x32_bf16 v[16:19], v[96:99], v[32:35], v[16:19]
	ds_read2_b64 v[96:99], v151 offset1:4
	s_waitcnt lgkmcnt(1)
	v_mfma_f32_16x16x32_bf16 v[20:23], v[48:51], v[32:35], v[20:23]
	ds_read2_b64 v[48:51], v158 offset0:128 offset1:132
	s_waitcnt lgkmcnt(1)
	v_mfma_f32_16x16x32_bf16 v[24:27], v[96:99], v[32:35], v[24:27]
	ds_read2_b64 v[96:99], v159 offset0:160 offset1:164
	s_waitcnt lgkmcnt(1)
	v_mfma_f32_16x16x32_bf16 v[48:51], v[48:51], v[32:35], v[52:55]
	s_nop 2
	ds_read2_b64 v[52:55], v157 offset0:192 offset1:196
	s_waitcnt lgkmcnt(1)
	v_mfma_f32_16x16x32_bf16 v[40:43], v[96:99], v[32:35], v[40:43]
	ds_read2_b64 v[96:99], v152 offset1:4
	s_waitcnt lgkmcnt(1)
	v_mfma_f32_16x16x32_bf16 v[52:55], v[52:55], v[32:35], v[60:63]
	s_nop 2
	ds_read2_b64 v[60:63], v154 offset1:4
	s_waitcnt lgkmcnt(1)
	v_mfma_f32_16x16x32_bf16 v[56:59], v[96:99], v[32:35], v[56:59]
	ds_read2_b64 v[96:99], v155 offset0:32 offset1:36
	s_waitcnt lgkmcnt(1)
	v_mfma_f32_16x16x32_bf16 v[60:63], v[60:63], v[32:35], v[72:75]
	s_nop 2
	ds_read2_b64 v[72:75], v153 offset0:64 offset1:68
	s_waitcnt lgkmcnt(1)
	v_mfma_f32_16x16x32_bf16 v[76:79], v[96:99], v[32:35], v[76:79]
	ds_read2_b64 v[96:99], v150 offset1:4
	s_waitcnt lgkmcnt(1)
	v_mfma_f32_16x16x32_bf16 v[72:75], v[72:75], v[32:35], v[80:83]
	s_nop 2
	ds_read2_b64 v[80:83], v139 offset0:128 offset1:132
	s_waitcnt lgkmcnt(1)
	v_mfma_f32_16x16x32_bf16 v[84:87], v[96:99], v[32:35], v[84:87]
	ds_read2_b64 v[96:99], v146 offset0:160 offset1:164
	s_waitcnt lgkmcnt(1)
	v_mfma_f32_16x16x32_bf16 v[68:71], v[80:83], v[32:35], v[68:71]
	ds_read2_b64 v[80:83], v144 offset0:192 offset1:196
	s_waitcnt lgkmcnt(1)
	v_mfma_f32_16x16x32_bf16 v[28:31], v[96:99], v[32:35], v[28:31]
	ds_read2_b64 v[96:99], v149 offset1:4
	s_waitcnt lgkmcnt(1)
	v_mfma_f32_16x16x32_bf16 v[64:67], v[80:83], v[32:35], v[64:67]
	ds_read2_b64 v[80:83], v156 offset0:8 offset1:12
	s_waitcnt lgkmcnt(1)
	v_mfma_f32_16x16x32_bf16 v[32:35], v[96:99], v[32:35], v[36:39]
	s_nop 2
	ds_read2_b64 v[36:39], v163 offset0:40 offset1:44
	s_waitcnt lgkmcnt(1)
	v_mfma_f32_16x16x32_bf16 v[12:15], v[80:83], v[8:11], v[12:15]
	ds_read2_b64 v[80:83], v162 offset0:72 offset1:76
	s_waitcnt lgkmcnt(1)
	v_mfma_f32_16x16x32_bf16 v[16:19], v[36:39], v[8:11], v[16:19]
	ds_read2_b64 v[36:39], v151 offset0:8 offset1:12
	s_waitcnt lgkmcnt(1)
	v_mfma_f32_16x16x32_bf16 v[20:23], v[80:83], v[8:11], v[20:23]
	ds_read2_b64 v[80:83], v158 offset0:136 offset1:140
	s_waitcnt lgkmcnt(1)
	v_mfma_f32_16x16x32_bf16 v[24:27], v[36:39], v[8:11], v[24:27]
	ds_read2_b64 v[36:39], v159 offset0:168 offset1:172
	s_waitcnt lgkmcnt(1)
	v_mfma_f32_16x16x32_bf16 v[48:51], v[80:83], v[8:11], v[48:51]
	ds_read2_b64 v[80:83], v157 offset0:200 offset1:204
	s_waitcnt lgkmcnt(1)
	v_mfma_f32_16x16x32_bf16 v[36:39], v[36:39], v[8:11], v[40:43]
	s_nop 2
	ds_read2_b64 v[40:43], v152 offset0:8 offset1:12
	s_waitcnt lgkmcnt(1)
	v_mfma_f32_16x16x32_bf16 v[52:55], v[80:83], v[8:11], v[52:55]
	ds_read2_b64 v[80:83], v154 offset0:8 offset1:12
	s_waitcnt lgkmcnt(1)
	v_mfma_f32_16x16x32_bf16 v[40:43], v[40:43], v[8:11], v[56:59]
	s_nop 2
	ds_read2_b64 v[56:59], v155 offset0:40 offset1:44
	s_waitcnt lgkmcnt(1)
	v_mfma_f32_16x16x32_bf16 v[60:63], v[80:83], v[8:11], v[60:63]
	ds_read2_b64 v[80:83], v153 offset0:72 offset1:76
	s_waitcnt lgkmcnt(1)
	v_mfma_f32_16x16x32_bf16 v[56:59], v[56:59], v[8:11], v[76:79]
	s_nop 2
	ds_read2_b64 v[76:79], v150 offset0:8 offset1:12
	s_waitcnt lgkmcnt(1)
	v_mfma_f32_16x16x32_bf16 v[72:75], v[80:83], v[8:11], v[72:75]
	ds_read2_b64 v[80:83], v139 offset0:136 offset1:140
	ds_read2_b64 v[96:99], v146 offset0:168 offset1:172
	s_waitcnt lgkmcnt(2)
	v_mfma_f32_16x16x32_bf16 v[76:79], v[76:79], v[8:11], v[84:87]
	s_nop 2
	ds_read2_b64 v[84:87], v144 offset0:200 offset1:204
	ds_read2_b64 v[104:107], v149 offset0:8 offset1:12
	s_waitcnt vmcnt(3)
	ds_write_b128 v176, v[44:47] offset:36864
	s_waitcnt vmcnt(2)
	ds_write_b128 v160, v[88:91] offset:36864
	s_waitcnt vmcnt(1)
	ds_write_b128 v161, v[100:103] offset:36864
	s_waitcnt vmcnt(0)
	ds_write_b128 v148, v[92:95] offset:36864
	s_waitcnt lgkmcnt(7)
	v_mfma_f32_16x16x32_bf16 v[44:47], v[80:83], v[8:11], v[68:71]
	s_waitcnt lgkmcnt(0)
	s_barrier
; #define LAS __attribute__((address_space(3)))
; __device__ __forceinline__ unsigned pk2(float lo, float hi) { f32x2_t v = {lo, hi}; bf16x2_t b = __builtin_convertvector(v, bf16x2_t); return __builtin_bit_cast(unsigned, b); }
; __device__ __forceinline__ f32x4 mfma16(bf16x8 a, bf16x8 b, f32x4 c) { return __builtin_amdgcn_mfma_f32_16x16x32_bf16(a, b, c, 0, 0, 0); }
; __device__ __forceinline__ void xattn_unit(const Args& a, LAS unsigned char* lds, int b, int h, int qb, int tid, int wave, int lane) {
;     ...
;         } else {
;             const int mt = j - 4;
; #pragma unroll
;             for (int dt = 0; dt < 16; ++dt) {
;                 const LAS bf16* vr = base + (16 * dt + fr) * VS + 4 * fq;
;                 O[dt] = mfma16(cat8(*(const LAS u32x2*)vr, *(const LAS u32x2*)(vr + 16)), pf[2 * mt], O[dt]);
;                 O[dt] = mfma16(cat8(*(const LAS u32x2*)(vr + 32), *(const LAS u32x2*)(vr + 48)), pf[2 * mt + 1], O[dt]);
;             }
;         }
;         if (j < 7) lstore(j + 1);
;         __syncthreads();
;     }
;     const float il = 1.f / l;
; #pragma unroll
;     for (int dt = 0; dt < 16; ++dt) { u32x2 w; w.x = pk2(O[dt][0] * il, O[dt][1] * il); w.y = pk2(O[dt][2] * il, O[dt][3] * il);
	v_mfma_f32_16x16x32_bf16 v[28:31], v[96:99], v[8:11], v[28:31]
	ds_read2_b64 v[68:71], v138 offset1:4
	v_mfma_f32_16x16x32_bf16 v[64:67], v[84:87], v[8:11], v[64:67]
	v_mfma_f32_16x16x32_bf16 v[8:11], v[104:107], v[8:11], v[32:35]
	s_nop 2
	ds_read2_b64 v[32:35], v145 offset0:32 offset1:36
	s_waitcnt lgkmcnt(1)
	v_mfma_f32_16x16x32_bf16 v[12:15], v[68:71], v[4:7], v[12:15]
	ds_read2_b64 v[68:71], v147 offset0:64 offset1:68
	s_waitcnt lgkmcnt(1)
	v_mfma_f32_16x16x32_bf16 v[16:19], v[32:35], v[4:7], v[16:19]
	ds_read2_b64 v[32:35], v164 offset1:4
	s_waitcnt lgkmcnt(1)
	v_mfma_f32_16x16x32_bf16 v[20:23], v[68:71], v[4:7], v[20:23]
	ds_read2_b64 v[68:71], v165 offset0:128 offset1:132
	s_waitcnt lgkmcnt(1)
	v_mfma_f32_16x16x32_bf16 v[24:27], v[32:35], v[4:7], v[24:27]
	ds_read2_b64 v[32:35], v166 offset0:160 offset1:164
	s_waitcnt lgkmcnt(1)
	v_mfma_f32_16x16x32_bf16 v[48:51], v[68:71], v[4:7], v[48:51]
	ds_read2_b64 v[68:71], v167 offset0:192 offset1:196
	s_waitcnt lgkmcnt(1)
	v_mfma_f32_16x16x32_bf16 v[32:35], v[32:35], v[4:7], v[36:39]
	s_nop 2
	ds_read2_b64 v[36:39], v168 offset1:4
	s_waitcnt lgkmcnt(1)
	v_mfma_f32_16x16x32_bf16 v[52:55], v[68:71], v[4:7], v[52:55]
	ds_read2_b64 v[68:71], v169 offset1:4
	s_waitcnt lgkmcnt(1)
	v_mfma_f32_16x16x32_bf16 v[36:39], v[36:39], v[4:7], v[40:43]
	s_nop 2
	ds_read2_b64 v[40:43], v170 offset0:32 offset1:36
	s_waitcnt lgkmcnt(1)
	v_mfma_f32_16x16x32_bf16 v[60:63], v[68:71], v[4:7], v[60:63]
	ds_read2_b64 v[68:71], v171 offset0:64 offset1:68
	s_waitcnt lgkmcnt(1)
	v_mfma_f32_16x16x32_bf16 v[40:43], v[40:43], v[4:7], v[56:59]
	s_nop 2
	ds_read2_b64 v[56:59], v172 offset1:4
	s_waitcnt lgkmcnt(1)
	v_mfma_f32_16x16x32_bf16 v[68:71], v[68:71], v[4:7], v[72:75]
	s_nop 2
	ds_read2_b64 v[72:75], v173 offset0:128 offset1:132
	s_waitcnt lgkmcnt(1)
	v_mfma_f32_16x16x32_bf16 v[56:59], v[56:59], v[4:7], v[76:79]
	s_nop 2
	ds_read2_b64 v[76:79], v177 offset0:160 offset1:164
	s_waitcnt lgkmcnt(1)
	v_mfma_f32_16x16x32_bf16 v[44:47], v[72:75], v[4:7], v[44:47]
	ds_read2_b64 v[72:75], v175 offset0:192 offset1:196
	s_waitcnt lgkmcnt(1)
	v_mfma_f32_16x16x32_bf16 v[28:31], v[76:79], v[4:7], v[28:31]
	ds_read2_b64 v[76:79], v174 offset1:4
	s_waitcnt lgkmcnt(1)
	v_mfma_f32_16x16x32_bf16 v[64:67], v[72:75], v[4:7], v[64:67]
	ds_read2_b64 v[72:75], v138 offset0:8 offset1:12
	s_waitcnt lgkmcnt(1)
	v_mfma_f32_16x16x32_bf16 v[4:7], v[76:79], v[4:7], v[8:11]
	s_nop 2
	ds_read2_b64 v[8:11], v145 offset0:40 offset1:44
	s_waitcnt lgkmcnt(1)
	v_mfma_f32_16x16x32_bf16 v[12:15], v[72:75], v[0:3], v[12:15]
	ds_read2_b64 v[72:75], v147 offset0:72 offset1:76
	s_waitcnt lgkmcnt(1)
	v_mfma_f32_16x16x32_bf16 v[8:11], v[8:11], v[0:3], v[16:19]
	s_nop 2
	ds_read2_b64 v[16:19], v164 offset0:8 offset1:12
	s_waitcnt lgkmcnt(1)
	v_mfma_f32_16x16x32_bf16 v[20:23], v[72:75], v[0:3], v[20:23]
	ds_read2_b64 v[72:75], v165 offset0:136 offset1:140
	s_nop 0
	v_pk_mul_f32 v[8:9], v[120:121], v[8:9] op_sel_hi:[0,1]
	v_pk_mul_f32 v[10:11], v[120:121], v[10:11] op_sel_hi:[0,1]
	s_waitcnt lgkmcnt(1)
	v_mfma_f32_16x16x32_bf16 v[16:19], v[16:19], v[0:3], v[24:27]
	s_nop 2
	ds_read2_b64 v[24:27], v166 offset0:168 offset1:172
	s_waitcnt lgkmcnt(1)
	v_mfma_f32_16x16x32_bf16 v[48:51], v[72:75], v[0:3], v[48:51]
	ds_read2_b64 v[72:75], v167 offset0:200 offset1:204
	s_nop 0
	v_pk_mul_f32 v[16:17], v[120:121], v[16:17] op_sel_hi:[0,1]
	v_pk_mul_f32 v[18:19], v[120:121], v[18:19] op_sel_hi:[0,1]
	s_waitcnt lgkmcnt(1)
	v_mfma_f32_16x16x32_bf16 v[24:27], v[24:27], v[0:3], v[32:35]
	s_nop 2
	ds_read2_b64 v[32:35], v168 offset0:8 offset1:12
	s_waitcnt lgkmcnt(1)
	v_mfma_f32_16x16x32_bf16 v[52:55], v[72:75], v[0:3], v[52:55]
	ds_read2_b64 v[72:75], v169 offset0:8 offset1:12
	s_nop 0
	v_pk_mul_f32 v[24:25], v[120:121], v[24:25] op_sel_hi:[0,1]
	v_pk_mul_f32 v[26:27], v[120:121], v[26:27] op_sel_hi:[0,1]
	s_waitcnt lgkmcnt(1)
	v_mfma_f32_16x16x32_bf16 v[32:35], v[32:35], v[0:3], v[36:39]
	s_nop 2
	ds_read2_b64 v[36:39], v170 offset0:40 offset1:44
	s_waitcnt lgkmcnt(1)
	v_mfma_f32_16x16x32_bf16 v[60:63], v[72:75], v[0:3], v[60:63]
	ds_read2_b64 v[72:75], v171 offset0:72 offset1:76
	s_nop 0
	v_pk_mul_f32 v[32:33], v[120:121], v[32:33] op_sel_hi:[0,1]
	v_pk_mul_f32 v[34:35], v[120:121], v[34:35] op_sel_hi:[0,1]
	s_waitcnt lgkmcnt(1)
	v_mfma_f32_16x16x32_bf16 v[36:39], v[36:39], v[0:3], v[40:43]
	s_nop 2
	ds_read2_b64 v[40:43], v172 offset0:8 offset1:12
	s_waitcnt lgkmcnt(1)
	v_mfma_f32_16x16x32_bf16 v[68:71], v[72:75], v[0:3], v[68:71]
	ds_read2_b64 v[72:75], v173 offset0:136 offset1:140
	s_nop 0
	v_pk_mul_f32 v[36:37], v[120:121], v[36:37] op_sel_hi:[0,1]
	v_pk_mul_f32 v[38:39], v[120:121], v[38:39] op_sel_hi:[0,1]
	s_waitcnt lgkmcnt(1)
	v_mfma_f32_16x16x32_bf16 v[40:43], v[40:43], v[0:3], v[56:59]
	s_nop 2
	ds_read2_b64 v[56:59], v177 offset0:168 offset1:172
	s_waitcnt lgkmcnt(1)
	v_mfma_f32_16x16x32_bf16 v[44:47], v[72:75], v[0:3], v[44:47]
	ds_read2_b64 v[72:75], v175 offset0:200 offset1:204
	s_nop 0
	v_pk_mul_f32 v[40:41], v[120:121], v[40:41] op_sel_hi:[0,1]
	v_pk_mul_f32 v[42:43], v[120:121], v[42:43] op_sel_hi:[0,1]
	s_waitcnt lgkmcnt(1)
	v_mfma_f32_16x16x32_bf16 v[28:31], v[56:59], v[0:3], v[28:31]
	ds_read2_b64 v[56:59], v174 offset0:8 offset1:12
	s_nop 0
	v_pk_mul_f32 v[44:45], v[120:121], v[44:45] op_sel_hi:[0,1]
	v_pk_mul_f32 v[46:47], v[120:121], v[46:47] op_sel_hi:[0,1]
	s_waitcnt lgkmcnt(1)
	v_mfma_f32_16x16x32_bf16 v[64:67], v[72:75], v[0:3], v[64:67]
	s_nop 1
	v_mul_f32_e64 v28, v120, v28
	v_mul_f32_e64 v29, v120, v29
	v_pk_mul_f32 v[30:31], v[120:121], v[30:31] op_sel_hi:[0,1]
	s_waitcnt lgkmcnt(0)
	v_mfma_f32_16x16x32_bf16 v[0:3], v[56:59], v[0:3], v[4:7]
	v_mul_f32_e64 v56, v120, v68
	v_mul_f32_e64 v57, v120, v69
	s_nop 0
	v_pk_mul_f32 v[4:5], v[120:121], v[12:13] op_sel_hi:[0,1]
	v_pk_mul_f32 v[6:7], v[120:121], v[14:15] op_sel_hi:[0,1]
	v_pk_mul_f32 v[12:13], v[120:121], v[20:21] op_sel_hi:[0,1]
	v_pk_mul_f32 v[14:15], v[120:121], v[22:23] op_sel_hi:[0,1]
	v_pk_mul_f32 v[20:21], v[120:121], v[48:49] op_sel_hi:[0,1]
	v_pk_mul_f32 v[22:23], v[120:121], v[50:51] op_sel_hi:[0,1]
	v_pk_mul_f32 v[48:49], v[120:121], v[52:53] op_sel_hi:[0,1]
	v_pk_mul_f32 v[50:51], v[120:121], v[54:55] op_sel_hi:[0,1]
	v_pk_mul_f32 v[52:53], v[120:121], v[60:61] op_sel_hi:[0,1]
	v_pk_mul_f32 v[54:55], v[120:121], v[62:63] op_sel_hi:[0,1]
	v_pk_mul_f32 v[58:59], v[120:121], v[70:71] op_sel_hi:[0,1]
	v_pk_mul_f32 v[60:61], v[120:121], v[64:65] op_sel_hi:[0,1]
	v_pk_mul_f32 v[62:63], v[120:121], v[66:67] op_sel_hi:[0,1]
	v_pk_mul_f32 v[0:1], v[120:121], v[0:1] op_sel_hi:[0,1]
	v_pk_mul_f32 v[2:3], v[120:121], v[2:3] op_sel_hi:[0,1]
	v_cvt_pk_bf16_f32 v4, v4, v5
	v_cvt_pk_bf16_f32 v5, v6, v7
	s_barrier
; #define GAS __attribute__((address_space(1)))
; __device__ __forceinline__ unsigned pk2(float lo, float hi) { f32x2_t v = {lo, hi}; bf16x2_t b = __builtin_convertvector(v, bf16x2_t); return __builtin_bit_cast(unsigned, b); }
; __device__ __forceinline__ unsigned xb_add(unsigned* p, unsigned v) { return __hip_atomic_fetch_add(p, v, __ATOMIC_RELAXED, __HIP_MEMORY_SCOPE_AGENT); }
; __device__ __forceinline__ void xattn_unit(const Args& a, LAS unsigned char* lds, int b, int h, int qb, int tid, int wave, int lane) {
;     ...
;     const float il = 1.f / l;
; #pragma unroll
;     for (int dt = 0; dt < 16; ++dt) { u32x2 w; w.x = pk2(O[dt][0] * il, O[dt][1] * il); w.y = pk2(O[dt][2] * il, O[dt][3] * il);
;         *(GAS u32x2*)(XO + qrow * DM + h * 256 + 16 * dt + 4 * fq) = w; }
; __device__ __forceinline__ void xcd_barrier(const XcdBarrier& b) {
;     asm volatile("s_waitcnt vmcnt(0)" ::: "memory");
;     __syncthreads();
;     if (threadIdx.x == 0) {
;         unsigned* bar = b.bar;
;         __builtin_amdgcn_s_waitcnt(0);
;         unsigned nloc = b.st[0], nx = b.st[1];
;         if (nloc == 0u) { xcd_barrier_complete(bar, b.x, nloc, nx); b.st[0] = nloc; b.st[1] = nx; }
;         const unsigned old = xb_add(&bar[XB_XSUB(b.x)], 1u);
;         const unsigned gen = old / nloc;
;         if (old + 1u == (gen + 1u) * nloc) {
	v_cvt_pk_bf16_f32 v6, v8, v9
	v_cvt_pk_bf16_f32 v7, v10, v11
	v_cvt_pk_bf16_f32 v8, v12, v13
	v_cvt_pk_bf16_f32 v9, v14, v15
	v_cvt_pk_bf16_f32 v10, v16, v17
	v_cvt_pk_bf16_f32 v11, v18, v19
	v_cvt_pk_bf16_f32 v12, v20, v21
	v_cvt_pk_bf16_f32 v13, v22, v23
	v_cvt_pk_bf16_f32 v14, v24, v25
	v_cvt_pk_bf16_f32 v15, v26, v27
	v_cvt_pk_bf16_f32 v16, v48, v49
	v_cvt_pk_bf16_f32 v17, v50, v51
	v_cvt_pk_bf16_f32 v18, v32, v33
	v_cvt_pk_bf16_f32 v19, v34, v35
	v_cvt_pk_bf16_f32 v20, v52, v53
	v_cvt_pk_bf16_f32 v21, v54, v55
	v_cvt_pk_bf16_f32 v22, v36, v37
	v_cvt_pk_bf16_f32 v23, v38, v39
	v_cvt_pk_bf16_f32 v24, v56, v57
	v_cvt_pk_bf16_f32 v25, v58, v59
	v_cvt_pk_bf16_f32 v26, v40, v41
	v_cvt_pk_bf16_f32 v27, v42, v43
	v_cvt_pk_bf16_f32 v36, v44, v45
	v_cvt_pk_bf16_f32 v37, v46, v47
	v_cvt_pk_bf16_f32 v38, v28, v29
	v_cvt_pk_bf16_f32 v39, v30, v31
	v_cvt_pk_bf16_f32 v40, v60, v61
	v_cvt_pk_bf16_f32 v41, v62, v63
	v_cvt_pk_bf16_f32 v42, v0, v1
	v_cvt_pk_bf16_f32 v43, v2, v3
	v_bfe_u32 v44, v252, 4, 1
	v_mul_u32_u24_e32 v44, 24, v44
	v_mov_b32_e32 v45, 0
	v_lshl_add_u64 v[44:45], v[136:137], 0, v[44:45]
	v_permlane16_swap_b32_e32 v4, v6
	v_permlane16_swap_b32_e32 v5, v7
	v_permlane16_swap_b32_e32 v8, v10
	v_permlane16_swap_b32_e32 v9, v11
	v_permlane16_swap_b32_e32 v12, v14
	v_permlane16_swap_b32_e32 v13, v15
	v_permlane16_swap_b32_e32 v16, v18
	v_permlane16_swap_b32_e32 v17, v19
	v_permlane16_swap_b32_e32 v20, v22
	v_permlane16_swap_b32_e32 v21, v23
	v_permlane16_swap_b32_e32 v24, v26
	v_permlane16_swap_b32_e32 v25, v27
	v_permlane16_swap_b32_e32 v36, v38
	v_permlane16_swap_b32_e32 v37, v39
	v_permlane16_swap_b32_e32 v40, v42
	v_permlane16_swap_b32_e32 v41, v43
	global_store_dwordx4 v[44:45], v[4:7], off
	global_store_dwordx4 v[44:45], v[8:11], off offset:64
	global_store_dwordx4 v[44:45], v[12:15], off offset:128
	global_store_dwordx4 v[44:45], v[16:19], off offset:192
	global_store_dwordx4 v[44:45], v[20:23], off offset:256
	global_store_dwordx4 v[44:45], v[24:27], off offset:320
	global_store_dwordx4 v[44:45], v[36:39], off offset:384
	global_store_dwordx4 v[44:45], v[40:43], off offset:448
	s_cbranch_scc0 .LBB0_1518
.LBB0_1519:
	s_setprio 0
	s_getreg_b32 s2, hwreg(HW_REG_XCC_ID, 0, 4)
	s_waitcnt vmcnt(0)
	s_barrier
	s_mov_b64 s[0:1], exec
	v_readlane_b32 s4, v254, 2
	v_readlane_b32 s5, v254, 3
	s_and_b64 s[4:5], s[0:1], s[4:5]
	s_mov_b64 exec, s[4:5]
	s_cbranch_execz .LBB0_1563
	s_add_i32 s3, 0, 0x200c0
	v_mov_b32_e32 v0, s3
	s_waitcnt vmcnt(0) expcnt(0) lgkmcnt(0)
	ds_read_b32 v2, v0
	s_add_i32 s3, 0, 0x200c4
	v_mov_b32_e32 v0, s3
	ds_read_b32 v0, v0
	s_and_b32 s33, s2, 15
	s_waitcnt lgkmcnt(1)
	v_cmp_ne_u32_e32 vcc, 0, v2
	s_cbranch_vccnz .LBB0_1534
	v_readlane_b32 s2, v254, 0
	v_readlane_b32 s3, v254, 1
	s_load_dwordx2 s[4:5], s[2:3], 0x4
	s_add_u32 s2, s72, 0xa0a200
	s_addc_u32 s3, s73, 0
	s_add_u32 s6, s72, 0xa0a400
	s_addc_u32 s7, s73, 0
	s_add_u32 s8, s72, 0xa0a500
	s_addc_u32 s9, s73, 0
	s_add_u32 s10, s72, 0xa0a600
	s_addc_u32 s11, s73, 0
	s_add_u32 s12, s72, 0xa0a700
	s_addc_u32 s13, s73, 0
	s_add_u32 s14, s72, 0xa0a800
	s_addc_u32 s15, s73, 0
	s_add_u32 s16, s72, 0xa0a900
	s_addc_u32 s17, s73, 0
	s_add_u32 s18, s72, 0xa0aa00
	s_addc_u32 s19, s73, 0
	s_add_u32 s20, s72, 0xa0ab00
	s_addc_u32 s21, s73, 0
	s_add_u32 s24, s72, 0xa0ac00
	s_addc_u32 s25, s73, 0
	s_add_u32 s26, s72, 0xa0ad00
	s_addc_u32 s27, s73, 0
	s_add_u32 s28, s72, 0xa0ae00
	s_addc_u32 s29, s73, 0
	s_add_u32 s30, s72, 0xa0af00
	s_addc_u32 s31, s73, 0
	s_add_u32 s34, s72, 0xa0b000
	s_addc_u32 s35, s73, 0
	s_add_u32 s36, s72, 0xa0b100
	s_addc_u32 s37, s73, 0
	s_add_u32 s38, s72, 0xa0b200
	s_addc_u32 s39, s73, 0
	s_add_u32 s40, s72, 0xa0b300
	s_waitcnt lgkmcnt(0)
	s_mul_i32 s22, s4, s76
	s_addc_u32 s41, s73, 0
	s_mul_i32 s22, s22, s5
	s_mov_b32 s23, 1
	s_mov_b64 s[4:5], 0
	v_mov_b64_e32 v[0:1], s[6:7]
	v_mov_b64_e32 v[2:3], s[8:9]
	v_mov_b64_e32 v[4:5], s[10:11]
	v_mov_b64_e32 v[6:7], s[12:13]
	v_mov_b64_e32 v[8:9], s[14:15]
	v_mov_b64_e32 v[10:11], s[16:17]
	v_mov_b64_e32 v[12:13], s[18:19]
	v_mov_b64_e32 v[14:15], s[20:21]
	v_mov_b64_e32 v[16:17], s[24:25]
	v_mov_b64_e32 v[18:19], s[26:27]
	v_mov_b64_e32 v[20:21], s[28:29]
	v_mov_b64_e32 v[22:23], s[30:31]
	v_mov_b64_e32 v[24:25], s[34:35]
	v_mov_b64_e32 v[26:27], s[36:37]
	v_mov_b64_e32 v[28:29], s[38:39]
	v_mov_b64_e32 v[30:31], s[40:41]
	s_branch .LBB0_1524
